# v8
# speedup vs baseline: 1.0160x; 1.0009x over previous
; template <int EPI>
; __device__ __forceinline__ void gemm_epi(const GemmArgs& G, const f32x4 (&a)[4][2], int rbase, int cbase, int fq, const float (&ssv)[4]) {
;     ...
;     const int row = rbase + m * 16;
;     float rs = 1.f;
;     if constexpr (EPI == EPI_GU || EPI == EPI_EVIN || EPI == EPI_ODIN) rs = rsqrtf(ssv[m] * (1.f / 2048.f) + 1e-6f);
;     ...
;             const int c = col - 4096;
;             if (c < 32) {
;               f32x4 bb = *reinterpret_cast<const f32x4*>(G.c0 + c);
;               f32x4 ov;
; #pragma unroll
;               for (int j = 0; j < 4; ++j) { float xx = v[j] + bb[j]; ov[j] = fmaxf(xx, 0.f) + __logf(1.f + __expf(-fabsf(xx))); }
;               *reinterpret_cast<f32x4*>(G.f0 + (size_t)row * 32 + c) = ov;
.LBB0_751:
	v_readfirstlane_b32 s6, v224
	s_andn2_b32 s6, s6, 63
	s_cmpk_gt_i32 s39, 0x7f
	v_add_u32_e32 v128, s6, v225
	s_mov_b32 s6, 0x800000
	v_and_b32_e32 v129, 15, v128
	v_ashrrev_i32_e32 v131, 2, v128
	v_and_or_b32 v155, v131, s85, v129
	v_lshrrev_b32_e32 v129, 1, v128
	v_and_b32_e32 v129, 0x60, v129
	v_lshrrev_b32_e32 v128, 2, v128
	v_and_or_b32 v128, v128, 12, v129
	s_waitcnt vmcnt(8)
	v_fmamk_f32 v129, v130, 0x3a000000, v229
	v_cmp_gt_f32_e32 vcc, s6, v129
	v_mul_f32_e32 v130, 0x4b800000, v129
	s_cselect_b64 s[42:43], -1, 0
	v_cndmask_b32_e32 v129, v129, v130, vcc
	v_rsq_f32_e32 v129, v129
	s_cmp_gt_i32 s39, 31
	v_add_u32_e32 v140, s40, v155
	s_cselect_b64 s[40:41], -1, 0
	s_and_b32 s53, s52, 0xffff
	v_mul_f32_e32 v130, 0x45800000, v129
	v_or_b32_e32 v180, s36, v128
	s_cmp_gt_u32 s53, 9
	v_cndmask_b32_e32 v134, v129, v130, vcc
	v_ashrrev_i32_e32 v141, 31, v140
	s_cselect_b64 s[38:39], -1, 0
	v_lshlrev_b64 v[130:131], 7, v[140:141]
	v_pk_mul_f32 v[136:137], v[134:135], v[126:127] op_sel_hi:[0,1]
	v_pk_mul_f32 v[138:139], v[134:135], v[124:125] op_sel_hi:[0,1]
	s_mov_b64 s[8:9], -1
	s_and_b64 vcc, exec, s[42:43]
	v_cmp_gt_i32_e64 s[6:7], s67, v180
	v_mov_b32_e32 v249, v245
	s_cbranch_vccz .LBB0_755
	s_and_saveexec_b64 s[8:9], s[6:7]
	s_cbranch_execz .LBB0_754
	s_movk_i32 s6, 0xc000
	v_ashrrev_i32_e32 v125, 31, v180
	v_mov_b32_e32 v124, v180
	s_mov_b32 s7, -1
	v_lshl_add_u64 v[132:133], v[124:125], 2, s[6:7]
	v_lshl_add_u64 v[124:125], s[16:17], 0, v[132:133]
	global_load_dwordx4 v[124:127], v[124:125], off
	s_mov_b32 s11, 0xbfb8aa3b
	s_mov_b32 s10, 0x800000
	s_mov_b32 s44, 0x3f317217
	s_waitcnt vmcnt(0)
	v_add_f32_e32 v129, v138, v124
	v_max_f32_e32 v124, 0, v129
	v_mul_f32_e64 v129, |v129|, s11
	v_exp_f32_e32 v129, v129
	s_nop 0
	v_add_f32_e32 v129, 1.0, v129
	v_cmp_gt_f32_e32 vcc, s10, v129
	s_nop 1
	v_cndmask_b32_e64 v135, 0, 32, vcc
	v_ldexp_f32 v129, v129, v135
	v_log_f32_e32 v129, v129
	s_nop 0
	v_mul_f32_e32 v135, 0x3f317217, v129
	v_fma_f32 v135, v129, s44, -v135
	v_fmac_f32_e32 v135, 0x3377d1cf, v129
	v_fmac_f32_e32 v135, 0x3f317217, v129
	v_cmp_lt_f32_e64 s[6:7], |v129|, s62
	s_nop 1
	v_cndmask_b32_e64 v129, v129, v135, s[6:7]
	v_cndmask_b32_e32 v135, 0, v251, vcc
	v_sub_f32_e32 v142, v129, v135
	v_add_f32_e32 v129, v139, v125
	v_max_f32_e32 v125, 0, v129
	v_mul_f32_e64 v129, |v129|, s11
	v_exp_f32_e32 v129, v129
	s_nop 0
	v_add_f32_e32 v129, 1.0, v129
	v_cmp_gt_f32_e32 vcc, s10, v129
	s_nop 1
	v_cndmask_b32_e64 v135, 0, 32, vcc
	v_ldexp_f32 v129, v129, v135
	v_log_f32_e32 v129, v129
	s_nop 0
	v_mul_f32_e32 v135, 0x3f317217, v129
	v_fma_f32 v135, v129, s44, -v135
	v_fmac_f32_e32 v135, 0x3377d1cf, v129
	v_fmac_f32_e32 v135, 0x3f317217, v129
	v_cmp_lt_f32_e64 s[6:7], |v129|, s62
	s_nop 1
	v_cndmask_b32_e64 v129, v129, v135, s[6:7]
	v_cndmask_b32_e32 v135, 0, v251, vcc
	v_sub_f32_e32 v143, v129, v135
	v_add_f32_e32 v129, v136, v126
	v_max_f32_e32 v126, 0, v129
	v_mul_f32_e64 v129, |v129|, s11
	v_exp_f32_e32 v129, v129
	v_pk_add_f32 v[124:125], v[124:125], v[142:143]
	v_lshl_add_u64 v[142:143], s[28:29], 0, v[130:131]
	v_lshl_add_u64 v[132:133], v[142:143], 0, v[132:133]
	v_add_f32_e32 v129, 1.0, v129
	v_cmp_gt_f32_e32 vcc, s10, v129
	s_nop 1
	v_cndmask_b32_e64 v135, 0, 32, vcc
	v_ldexp_f32 v129, v129, v135
	v_log_f32_e32 v129, v129
	s_nop 0
	v_mul_f32_e32 v135, 0x3f317217, v129
	v_fma_f32 v135, v129, s44, -v135
	v_fmac_f32_e32 v135, 0x3377d1cf, v129
	v_fmac_f32_e32 v135, 0x3f317217, v129
	v_cmp_lt_f32_e64 s[6:7], |v129|, s62
	s_nop 1
	v_cndmask_b32_e64 v129, v129, v135, s[6:7]
	v_cndmask_b32_e32 v135, 0, v251, vcc
	v_sub_f32_e32 v144, v129, v135
	v_add_f32_e32 v129, v137, v127
	v_max_f32_e32 v127, 0, v129
	v_mul_f32_e64 v129, |v129|, s11
	v_exp_f32_e32 v129, v129
	s_nop 0
	v_add_f32_e32 v129, 1.0, v129
	v_cmp_gt_f32_e32 vcc, s10, v129
	s_nop 1
	v_cndmask_b32_e64 v135, 0, 32, vcc
	v_ldexp_f32 v129, v129, v135
	v_log_f32_e32 v129, v129
	s_nop 0
	v_mul_f32_e32 v135, 0x3f317217, v129
	v_fma_f32 v135, v129, s44, -v135
	v_fmac_f32_e32 v135, 0x3377d1cf, v129
	v_fmac_f32_e32 v135, 0x3f317217, v129
	v_cmp_lt_f32_e64 s[6:7], |v129|, s62
	s_nop 1
	v_cndmask_b32_e64 v129, v129, v135, s[6:7]
	v_cndmask_b32_e32 v135, 0, v251, vcc
	v_sub_f32_e32 v145, v129, v135
	v_pk_add_f32 v[126:127], v[126:127], v[144:145]
	global_store_dwordx4 v[132:133], v[124:127], off

; __device__ __forceinline__ u32x2 pack4(f32x4 v) { u32x2 o = {cvtpk(v[0], v[1]), cvtpk(v[2], v[3])}; return o; }
; #define MFMA16(a, b, c) __builtin_amdgcn_mfma_f32_16x16x32_bf16(a, b, c, 0, 0, 0)
; __device__ __forceinline__ void ssd_item(const u16* __restrict__ XC, const float* __restrict__ DTF, u16* __restrict__ Y,
;                          int seq_start, int len, int h, int dir, float a_coef, char* lds) {
;     ...
;     { const float el = __expf(alast);
; #pragma unroll
;       for (int i = 0; i < 4; ++i) { Sacc[i][0] *= el; Sacc[i][1] *= el; Sacc[i][2] *= el; Sacc[i][3] *= el; }
; #pragma unroll
;       for (int ks = 0; ks < 4; ++ks) {
;         bf16x8 a = *reinterpret_cast<const bf16x8*>(xt_rd + pt_s * 16 * LS + ks * 32);
; #pragma unroll
;         for (int i = 0; i < 4; ++i) {
;           bf16x8 b = *reinterpret_cast<const bf16x8*>(bt_rd + i * 16 * LS + ks * 32);
;           Sacc[i] = MFMA16(b, a, Sacc[i]);
;         }
;       } }
;     __syncthreads();
; #pragma unroll
;     for (int i = 0; i < 4; ++i) *reinterpret_cast<u32x2*>(&Ps[(pt_s * 16 + fr) * LS + (ntb + i) * 16 + fq * 4]) = pack4(Sacc[i]);
.LBB0_1668:
	v_mov_b32_e32 v56, 0x3fb8aa3b
	v_mul_f32_e32 v56, s35, v56
	v_exp_f32_e32 v56, v56
	v_add_u32_e32 v119, 0x80, v119
	v_add_u32_e32 v120, 0x80, v120
	v_add_u32_e32 v121, 0xffffff80, v121
	v_pk_mul_f32 v[40:41], v[40:41], v[56:57] op_sel_hi:[1,0]
	v_pk_mul_f32 v[42:43], v[42:43], v[56:57] op_sel_hi:[1,0]
	v_pk_mul_f32 v[44:45], v[44:45], v[56:57] op_sel_hi:[1,0]
	v_pk_mul_f32 v[46:47], v[46:47], v[56:57] op_sel_hi:[1,0]
	v_pk_mul_f32 v[48:49], v[48:49], v[56:57] op_sel_hi:[1,0]
	v_pk_mul_f32 v[50:51], v[50:51], v[56:57] op_sel_hi:[1,0]
	v_pk_mul_f32 v[52:53], v[52:53], v[56:57] op_sel_hi:[1,0]
	v_pk_mul_f32 v[54:55], v[54:55], v[56:57] op_sel_hi:[1,0]
	ds_read_b128 v[136:139], v124
	ds_read_b128 v[140:143], v101
	ds_read_b128 v[144:147], v101 offset:4352
	ds_read_b128 v[148:151], v101 offset:8704
	ds_read_b128 v[152:155], v101 offset:13056
	ds_read_b128 v[156:159], v124 offset:64
	ds_read_b128 v[160:163], v101 offset:64
	ds_read_b128 v[164:167], v101 offset:4416
	ds_read_b128 v[168:171], v101 offset:8768
	ds_read_b128 v[172:175], v101 offset:13120
	v_add_u32_e32 v122, 0x80, v122
	v_add_u32_e32 v123, 0xffffff80, v123
	s_cmp_lg_u32 s34, s31
	s_waitcnt lgkmcnt(8)
	v_mfma_f32_16x16x32_bf16 v[40:43], v[140:143], v[136:139], v[40:43]
	s_waitcnt lgkmcnt(7)
	v_mfma_f32_16x16x32_bf16 v[44:47], v[144:147], v[136:139], v[44:47]
	s_waitcnt lgkmcnt(6)
	v_mfma_f32_16x16x32_bf16 v[48:51], v[148:151], v[136:139], v[48:51]
	s_waitcnt lgkmcnt(5)
	v_mfma_f32_16x16x32_bf16 v[52:55], v[152:155], v[136:139], v[52:55]
	ds_read_b128 v[136:139], v124 offset:128
	ds_read_b128 v[140:143], v101 offset:128
	ds_read_b128 v[144:147], v101 offset:4480
	ds_read_b128 v[148:151], v101 offset:8832
	ds_read_b128 v[152:155], v101 offset:13184
	s_waitcnt lgkmcnt(8)
	v_mfma_f32_16x16x32_bf16 v[40:43], v[160:163], v[156:159], v[40:43]
	s_waitcnt lgkmcnt(7)
	v_mfma_f32_16x16x32_bf16 v[44:47], v[164:167], v[156:159], v[44:47]
	s_waitcnt lgkmcnt(6)
	v_mfma_f32_16x16x32_bf16 v[48:51], v[168:171], v[156:159], v[48:51]
	s_waitcnt lgkmcnt(5)
	v_mfma_f32_16x16x32_bf16 v[52:55], v[172:175], v[156:159], v[52:55]
	ds_read_b128 v[156:159], v124 offset:192
	ds_read_b128 v[160:163], v101 offset:192
	ds_read_b128 v[164:167], v101 offset:4544
	ds_read_b128 v[168:171], v101 offset:8896
	ds_read_b128 v[172:175], v101 offset:13248
	s_waitcnt lgkmcnt(8)
	v_mfma_f32_16x16x32_bf16 v[40:43], v[140:143], v[136:139], v[40:43]
	s_waitcnt lgkmcnt(7)
	v_mfma_f32_16x16x32_bf16 v[44:47], v[144:147], v[136:139], v[44:47]
	s_waitcnt lgkmcnt(6)
	v_mfma_f32_16x16x32_bf16 v[48:51], v[148:151], v[136:139], v[48:51]
	s_waitcnt lgkmcnt(5)
	v_mfma_f32_16x16x32_bf16 v[52:55], v[152:155], v[136:139], v[52:55]
	s_waitcnt lgkmcnt(3)
	v_mfma_f32_16x16x32_bf16 v[40:43], v[160:163], v[156:159], v[40:43]
	s_waitcnt lgkmcnt(2)
	v_mfma_f32_16x16x32_bf16 v[44:47], v[164:167], v[156:159], v[44:47]
	s_waitcnt lgkmcnt(1)
	v_mfma_f32_16x16x32_bf16 v[48:51], v[168:171], v[156:159], v[48:51]
	s_waitcnt lgkmcnt(0)
	s_barrier
	v_mfma_f32_16x16x32_bf16 v[52:55], v[172:175], v[156:159], v[52:55]
	s_nop 1
	v_cvt_pk_bf16_f32 v56, v40, v41
	v_cvt_pk_bf16_f32 v57, v42, v43
	ds_write_b64 v125, v[56:57]
	v_cvt_pk_bf16_f32 v56, v44, v45
	v_cvt_pk_bf16_f32 v57, v46, v47
	ds_write_b64 v125, v[56:57] offset:32
	v_cvt_pk_bf16_f32 v56, v48, v49
	v_cvt_pk_bf16_f32 v57, v50, v51
	ds_write_b64 v125, v[56:57] offset:64
	v_cvt_pk_bf16_f32 v56, v52, v53
	v_cvt_pk_bf16_f32 v57, v54, v55
	ds_write_b64 v125, v[56:57] offset:96
	s_cbranch_scc0 .LBB0_1629

; __device__ __forceinline__ float bf2f(short v) { return __uint_as_float(((unsigned)(unsigned short)v) << 16); }
; __device__ __forceinline__ u16 f2bf(float f) { return (u16)(cvtpk(f, f) & 0xffffu); }
; __device__ __forceinline__ float shi(float v, int src) { return __int_as_float(__builtin_amdgcn_ds_bpermute(src << 2, __float_as_int(v))); }
; __device__ __forceinline__ void ssd_item(const u16* __restrict__ XC, const float* __restrict__ DTF, u16* __restrict__ Y,
;                          int seq_start, int len, int h, int dir, float a_coef, char* lds) {
;     ...
;     { const int sl = lst >> 1;
;       const float a_e = shi(acs0, sl), a_o = shi(acs1, sl), d_e = shi(dt0, sl), d_o = shi(dt1, sl);
;       const float acs_l = (lst & 1) ? a_o : a_e, dt_l = (lst & 1) ? d_o : d_e;
;       const float wl = dt_l * __expf(alast - acs_l);
;       if (w == 0) { acsL[2 * lane] = acs0; acsL[2 * lane + 1] = acs1; dtL[2 * lane] = dt0; dtL[2 * lane + 1] = dt1; }
; #pragma unroll
;       for (int i = 0; i < 4; ++i) {
;         *reinterpret_cast<bf16x8*>(&Cs[lst * LS + (i * 4 + fq) * 8]) = cR[i];
;         *reinterpret_cast<bf16x8*>(&Bs[lst * LS + (i * 4 + fq) * 8]) = bR[i];
; #pragma unroll
;         for (int e = 0; e < 8; ++e) BTs[((i * 4 + fq) * 8 + e) * LS + lst] = f2bf(bf2f(bR[i][e]) * wl);
;       }
; #pragma unroll
;       for (int i = 0; i < 2; ++i)
; #pragma unroll
;         for (int e = 0; e < 8; ++e) xT[((i * 4 + fq) * 8 + e) * LS + lst] = (u16)xR[i][e];
;     }
;     __syncthreads();
.LBB0_1671:
	s_or_b64 exec, exec, s[26:27]
	s_waitcnt lgkmcnt(0)
	v_cndmask_b32_e64 v56, v59, v60, s[6:7]
	v_sub_f32_e32 v56, s35, v56
	v_mul_f32_e32 v56, 0x3fb8aa3b, v56
	v_exp_f32_e32 v56, v56
	v_cndmask_b32_e64 v57, v61, v58, s[6:7]
	ds_write_b128 v116, v[0:3]
	ds_write_b128 v116, v[4:7] offset:34816
	v_add_u32_e32 v58, v106, v117
	v_mul_f32_e32 v56, v56, v57
	v_lshlrev_b32_e32 v57, 16, v4
	v_mul_f32_e32 v57, v56, v57
	v_cvt_pk_bf16_f32 v57, v57, v57
	ds_write_b16 v58, v57
	v_and_b32_e32 v57, 0xffff0000, v4
	v_mul_f32_e32 v57, v56, v57
	v_cvt_pk_bf16_f32 v57, v57, v57
	ds_write_b16 v58, v57 offset:272
	v_lshlrev_b32_e32 v57, 16, v5
	v_mul_f32_e32 v57, v56, v57
	v_cvt_pk_bf16_f32 v57, v57, v57
	ds_write_b16 v58, v57 offset:544
	v_and_b32_e32 v57, 0xffff0000, v5
	v_mul_f32_e32 v57, v56, v57
	v_cvt_pk_bf16_f32 v57, v57, v57
	ds_write_b16 v58, v57 offset:816
	v_lshlrev_b32_e32 v57, 16, v6
	v_mul_f32_e32 v57, v56, v57
	v_cvt_pk_bf16_f32 v57, v57, v57
	ds_write_b16 v58, v57 offset:1088
	v_and_b32_e32 v57, 0xffff0000, v6
	v_mul_f32_e32 v57, v56, v57
	v_cvt_pk_bf16_f32 v57, v57, v57
	ds_write_b16 v58, v57 offset:1360
	v_lshlrev_b32_e32 v57, 16, v7
	v_mul_f32_e32 v57, v56, v57
	v_cvt_pk_bf16_f32 v57, v57, v57
	ds_write_b16 v58, v57 offset:1632
	v_and_b32_e32 v57, 0xffff0000, v7
	v_mul_f32_e32 v57, v56, v57
	v_cvt_pk_bf16_f32 v57, v57, v57
	ds_write_b16 v58, v57 offset:1904
	ds_write_b128 v116, v[8:11] offset:64
	ds_write_b128 v116, v[12:15] offset:34880
	v_lshlrev_b32_e32 v57, 16, v12
	v_mul_f32_e32 v57, v56, v57
	v_cvt_pk_bf16_f32 v57, v57, v57
	v_add_u32_e32 v59, v106, v118
	ds_write_b16 v59, v57
	v_and_b32_e32 v57, 0xffff0000, v12
	v_mul_f32_e32 v57, v56, v57
	v_cvt_pk_bf16_f32 v57, v57, v57
	ds_write_b16 v58, v57 offset:8976
	v_lshlrev_b32_e32 v57, 16, v13
	v_mul_f32_e32 v57, v56, v57
	v_cvt_pk_bf16_f32 v57, v57, v57
	ds_write_b16 v58, v57 offset:9248
	v_and_b32_e32 v57, 0xffff0000, v13
	v_mul_f32_e32 v57, v56, v57
	v_cvt_pk_bf16_f32 v57, v57, v57
	ds_write_b16 v58, v57 offset:9520
	v_lshlrev_b32_e32 v57, 16, v14
	v_mul_f32_e32 v57, v56, v57
	v_cvt_pk_bf16_f32 v57, v57, v57
	ds_write_b16 v58, v57 offset:9792
	v_and_b32_e32 v57, 0xffff0000, v14
	v_mul_f32_e32 v57, v56, v57
	v_cvt_pk_bf16_f32 v57, v57, v57
	ds_write_b16 v58, v57 offset:10064
	v_lshlrev_b32_e32 v57, 16, v15
	v_mul_f32_e32 v57, v56, v57
	v_cvt_pk_bf16_f32 v57, v57, v57
	ds_write_b16 v58, v57 offset:10336
	v_and_b32_e32 v57, 0xffff0000, v15
	v_mul_f32_e32 v57, v56, v57
	v_cvt_pk_bf16_f32 v57, v57, v57
	ds_write_b16 v58, v57 offset:10608
	ds_write_b128 v116, v[16:19] offset:128
	ds_write_b128 v116, v[20:23] offset:34944
	v_lshlrev_b32_e32 v57, 16, v20
	v_mul_f32_e32 v57, v56, v57
	v_cvt_pk_bf16_f32 v57, v57, v57
	ds_write_b16 v59, v57 offset:8704
	v_and_b32_e32 v57, 0xffff0000, v20
	v_mul_f32_e32 v57, v56, v57
	v_cvt_pk_bf16_f32 v57, v57, v57
	ds_write_b16 v58, v57 offset:17680
	v_lshlrev_b32_e32 v57, 16, v21
	v_mul_f32_e32 v57, v56, v57
	v_cvt_pk_bf16_f32 v57, v57, v57
	ds_write_b16 v58, v57 offset:17952
	v_and_b32_e32 v57, 0xffff0000, v21
	v_mul_f32_e32 v57, v56, v57
	v_cvt_pk_bf16_f32 v57, v57, v57
	ds_write_b16 v58, v57 offset:18224
	v_lshlrev_b32_e32 v57, 16, v22
	v_mul_f32_e32 v57, v56, v57
	v_cvt_pk_bf16_f32 v57, v57, v57
	ds_write_b16 v58, v57 offset:18496
	v_and_b32_e32 v57, 0xffff0000, v22
	v_mul_f32_e32 v57, v56, v57
	v_cvt_pk_bf16_f32 v57, v57, v57
	ds_write_b16 v58, v57 offset:18768
	v_lshlrev_b32_e32 v57, 16, v23
	v_mul_f32_e32 v57, v56, v57
	v_cvt_pk_bf16_f32 v57, v57, v57
	ds_write_b16 v58, v57 offset:19040
	v_and_b32_e32 v57, 0xffff0000, v23
	v_mul_f32_e32 v57, v56, v57
	v_cvt_pk_bf16_f32 v57, v57, v57
	ds_write_b16 v58, v57 offset:19312
	ds_write_b128 v116, v[24:27] offset:192
	ds_write_b128 v116, v[28:31] offset:35008
	v_lshlrev_b32_e32 v57, 16, v28
	v_mul_f32_e32 v57, v56, v57
	v_cvt_pk_bf16_f32 v57, v57, v57
	ds_write_b16 v59, v57 offset:17408
	v_and_b32_e32 v57, 0xffff0000, v28
	v_mul_f32_e32 v57, v56, v57
	v_cvt_pk_bf16_f32 v57, v57, v57
	ds_write_b16 v58, v57 offset:26384
	v_lshlrev_b32_e32 v57, 16, v29
	v_mul_f32_e32 v57, v56, v57
	v_cvt_pk_bf16_f32 v57, v57, v57
	ds_write_b16 v58, v57 offset:26656
	v_and_b32_e32 v57, 0xffff0000, v29
	v_mul_f32_e32 v57, v56, v57
	v_cvt_pk_bf16_f32 v57, v57, v57
	ds_write_b16 v58, v57 offset:26928
	v_lshlrev_b32_e32 v57, 16, v30
	v_mul_f32_e32 v57, v56, v57
	v_cvt_pk_bf16_f32 v57, v57, v57
	ds_write_b16 v58, v57 offset:27200
	v_and_b32_e32 v57, 0xffff0000, v30
	v_mul_f32_e32 v57, v56, v57
	v_cvt_pk_bf16_f32 v57, v57, v57
	ds_write_b16 v58, v57 offset:27472
	v_lshlrev_b32_e32 v57, 16, v31
	v_mul_f32_e32 v57, v56, v57
	v_cvt_pk_bf16_f32 v57, v57, v57
	ds_write_b16 v58, v57 offset:27744
	v_and_b32_e32 v57, 0xffff0000, v31
	v_mul_f32_e32 v56, v56, v57
	v_cvt_pk_bf16_f32 v56, v56, v56
	ds_write_b16 v58, v56 offset:28016
	v_add_u32_e32 v56, v107, v117
	v_add_u32_e32 v57, v107, v118
	ds_write_b16 v56, v32
	ds_write_b16_d16_hi v56, v32 offset:272
	ds_write_b16 v56, v33 offset:544
	ds_write_b16_d16_hi v56, v33 offset:816
	ds_write_b16 v56, v34 offset:1088
	ds_write_b16_d16_hi v56, v34 offset:1360
	ds_write_b16 v56, v35 offset:1632
	ds_write_b16_d16_hi v56, v35 offset:1904
	ds_write_b16 v57, v36
	ds_write_b16_d16_hi v56, v36 offset:8976
	ds_write_b16 v56, v37 offset:9248
	ds_write_b16_d16_hi v56, v37 offset:9520
	ds_write_b16 v56, v38 offset:9792
	ds_write_b16_d16_hi v56, v38 offset:10064
	ds_write_b16 v56, v39 offset:10336
	ds_write_b16_d16_hi v56, v39 offset:10608
	s_waitcnt lgkmcnt(0)
	s_barrier
; #define MFMA16(a, b, c) __builtin_amdgcn_mfma_f32_16x16x32_bf16(a, b, c, 0, 0, 0)
; __device__ __forceinline__ void ssd_item(const u16* __restrict__ XC, const float* __restrict__ DTF, u16* __restrict__ Y,
;                          int seq_start, int len, int h, int dir, float a_coef, char* lds) {
;     ...
;     bf16x8 aC[4]; f32x4 yacc[4] = {};
; #pragma unroll
;     for (int ks = 0; ks < 4; ++ks) aC[ks] = *reinterpret_cast<const bf16x8*>(cs_row + ks * 32);
; #pragma unroll
;     for (int ks = 0; ks < 4; ++ks)
; #pragma unroll
;       for (int pt = 0; pt < 4; ++pt) {
;         bf16x8 b = *reinterpret_cast<const bf16x8*>(ps_rd + pt * 16 * LS + ks * 32);
;         yacc[pt] = MFMA16(b, aC[ks], yacc[pt]);
;       }
;     const float acs_row = acsL[R + fr], eal = __expf(acs_row);
	ds_read_b128 v[68:71], v97
	ds_read_b128 v[72:75], v98
	ds_read_b128 v[76:79], v98 offset:4352
	ds_read_b128 v[80:83], v98 offset:8704
	ds_read_b128 v[84:87], v98 offset:13056
	ds_read_b128 v[64:67], v97 offset:64
	ds_read_b128 v[136:139], v98 offset:64
	ds_read_b128 v[140:143], v98 offset:4416
	ds_read_b128 v[144:147], v98 offset:8768
	ds_read_b128 v[148:151], v98 offset:13120
	s_waitcnt lgkmcnt(8)
	v_mfma_f32_16x16x32_bf16 v[72:75], v[72:75], v[68:71], 0
	s_waitcnt lgkmcnt(7)
	v_mfma_f32_16x16x32_bf16 v[76:79], v[76:79], v[68:71], 0
	s_waitcnt lgkmcnt(6)
	v_mfma_f32_16x16x32_bf16 v[80:83], v[80:83], v[68:71], 0
	s_waitcnt lgkmcnt(5)
	v_mfma_f32_16x16x32_bf16 v[84:87], v[84:87], v[68:71], 0
	ds_read_b128 v[60:63], v97 offset:128
	ds_read_b128 v[152:155], v98 offset:128
	ds_read_b128 v[156:159], v98 offset:4480
	ds_read_b128 v[160:163], v98 offset:8832
	ds_read_b128 v[164:167], v98 offset:13184
	s_waitcnt lgkmcnt(8)
	v_mfma_f32_16x16x32_bf16 v[72:75], v[136:139], v[64:67], v[72:75]
	s_waitcnt lgkmcnt(7)
	v_mfma_f32_16x16x32_bf16 v[76:79], v[140:143], v[64:67], v[76:79]
	s_waitcnt lgkmcnt(6)
	v_mfma_f32_16x16x32_bf16 v[80:83], v[144:147], v[64:67], v[80:83]
	s_waitcnt lgkmcnt(5)
	v_mfma_f32_16x16x32_bf16 v[84:87], v[148:151], v[64:67], v[84:87]
	ds_read_b128 v[56:59], v97 offset:192
	ds_read_b128 v[136:139], v98 offset:192
	ds_read_b128 v[140:143], v98 offset:4544
	ds_read_b128 v[144:147], v98 offset:8896
	ds_read_b128 v[148:151], v98 offset:13248
	ds_read_b32 v126, v108
	s_waitcnt lgkmcnt(9)
	v_mfma_f32_16x16x32_bf16 v[72:75], v[152:155], v[60:63], v[72:75]
	s_waitcnt lgkmcnt(8)
	v_mfma_f32_16x16x32_bf16 v[76:79], v[156:159], v[60:63], v[76:79]
	s_waitcnt lgkmcnt(7)
	v_mfma_f32_16x16x32_bf16 v[80:83], v[160:163], v[60:63], v[80:83]
	s_waitcnt lgkmcnt(6)
	v_mfma_f32_16x16x32_bf16 v[84:87], v[164:167], v[60:63], v[84:87]
	s_waitcnt lgkmcnt(4)
	v_mfma_f32_16x16x32_bf16 v[72:75], v[136:139], v[56:59], v[72:75]
	s_waitcnt lgkmcnt(3)
	v_mfma_f32_16x16x32_bf16 v[76:79], v[140:143], v[56:59], v[76:79]
	s_waitcnt lgkmcnt(2)
	v_mfma_f32_16x16x32_bf16 v[80:83], v[144:147], v[56:59], v[80:83]
	s_waitcnt lgkmcnt(0)
	v_mfma_f32_16x16x32_bf16 v[84:87], v[148:151], v[56:59], v[84:87]
	s_and_saveexec_b64 s[26:27], s[42:43]
	s_cbranch_execnz .LBB0_1678
	s_or_b64 exec, exec, s[26:27]
	s_and_saveexec_b64 s[26:27], s[36:37]
	s_cbranch_execnz .LBB0_1681

; __device__ __forceinline__ float silu_f(float x) { return x * __builtin_amdgcn_rcpf(1.f + __builtin_amdgcn_exp2f(-1.4426950408889634f * x)); }
; template <int EPI>
; __device__ __forceinline__ void gemm_epi(const GemmArgs& G, const f32x4 (&a)[4][2], int rbase, int cbase, int fq, const float (&ssv)[4]) {
;     ...
;     const int row = rbase + m * 16;
;     float rs = 1.f;
;     if constexpr (EPI == EPI_GU || EPI == EPI_EVIN || EPI == EPI_ODIN) rs = rsqrtf(ssv[m] * (1.f / 2048.f) + 1e-6f);
;     if constexpr (EPI == EPI_GU) {
;       const f32x4 gv = a[m][0] * rs, uv = a[m][1] * rs;
;       const int hc = (cbase >> 1) + fq * 4;
;       u32x2 o = {cvtpk(silu_f(gv[0]) * uv[0], silu_f(gv[1]) * uv[1]), cvtpk(silu_f(gv[2]) * uv[2], silu_f(gv[3]) * uv[3])};
;       *reinterpret_cast<u32x2*>(G.d0 + (size_t)(row - G.row0) * DFF + hc) = o;
;     } else {
; #pragma unroll
;       for (int n = 0; n < 2; ++n) {
;         const f32x4 v = a[m][n] * rs;
;         const int col = cbase + n * 16 + fq * 4;
;         if constexpr (EPI == EPI_POOL) {
;           const int cg_ = G.aux * 256 + col;
;           f32x4 sc = *reinterpret_cast<const f32x4*>(G.c0 + cg_);
;           u32x2 o = {cvtpk(v[0] * sc[0], v[1] * sc[1]), cvtpk(v[2] * sc[2], v[3] * sc[3])};
;           *reinterpret_cast<u32x2*>(G.d0 + (size_t)row * 1024 + cg_) = o;
;         } else if constexpr (EPI == EPI_EVIN) {
;           u32x2 o = {cvtpk(v[0], v[1]), cvtpk(v[2], v[3])};
;           u16* dp;
;           if (tn < 4) dp = G.d0 + (size_t)row * 1024 + col;
;           else if (tn < 8) dp = G.d1 + (size_t)row * 1024 + (col - 1024);
;           else if (tn == 8) dp = G.d2 + (size_t)row * 256 + (col - 2048);
;           else dp = G.d3 + (size_t)row * 256 + (col - 2304);
;           *reinterpret_cast<u32x2*>(dp) = o;
.LBB0_1870:
	v_readfirstlane_b32 s6, v224
	s_andn2_b32 s6, s6, 63
	s_cmp_gt_i32 s34, 31
	v_add_u32_e32 v128, s6, v225
	s_cselect_b64 s[30:31], -1, 0
	v_and_b32_e32 v129, 15, v128
	v_ashrrev_i32_e32 v131, 2, v128
	v_and_or_b32 v146, v131, s85, v129
	v_lshrrev_b32_e32 v129, 1, v128
	v_and_b32_e32 v129, 0x60, v129
	v_lshrrev_b32_e32 v128, 2, v128
	s_and_b32 s6, s25, 0xff
	v_and_or_b32 v128, v128, 12, v129
	s_cmp_gt_u32 s6, 7
	s_waitcnt vmcnt(8)
	v_fmamk_f32 v129, v130, 0x3a000000, v229
	s_mov_b32 s6, 0x800000
	v_mul_f32_e32 v130, 0x4b800000, v129
	v_cmp_gt_f32_e32 vcc, s6, v129
	v_add_u32_e32 v138, s29, v146
	s_cselect_b64 s[28:29], -1, 0
	v_cndmask_b32_e32 v129, v129, v130, vcc
	v_rsq_f32_e32 v129, v129
	s_and_b32 s6, s34, 0xf8
	s_cmp_lg_u32 s6, 64
	v_ashrrev_i32_e32 v139, 31, v138
	v_mul_f32_e32 v130, 0x45800000, v129
	v_or_b32_e32 v180, s24, v128
	s_cselect_b64 s[26:27], -1, 0
	v_cndmask_b32_e32 v134, v129, v130, vcc
	v_lshlrev_b64 v[132:133], 9, v[138:139]
	v_lshlrev_b64 v[130:131], 11, v[138:139]
	s_mov_b64 s[6:7], -1
	s_and_b64 vcc, exec, s[30:31]
	v_mov_b32_e32 v249, v226
	v_pk_mul_f32 v[126:127], v[134:135], v[126:127] op_sel_hi:[0,1]
	v_pk_mul_f32 v[124:125], v[134:135], v[124:125] op_sel_hi:[0,1]
	v_cvt_pk_bf16_f32 v136, v124, v125
	v_cvt_pk_bf16_f32 v137, v126, v127
	s_cbranch_vccz .LBB0_1880
	s_and_b64 vcc, exec, s[28:29]
	s_cbranch_vccz .LBB0_1877
	s_and_b64 vcc, exec, s[26:27]
	s_cbranch_vccz .LBB0_1874
	v_lshl_add_u64 v[124:125], s[16:17], 0, v[132:133]
	s_movk_i32 s6, 0xee00
	v_lshl_add_u64 v[124:125], v[180:181], 1, v[124:125]
	s_mov_b32 s7, -1
	v_lshl_add_u64 v[140:141], v[124:125], 0, s[6:7]
	s_mov_b64 s[6:7], 0

; __device__ __forceinline__ float silu_f(float x) { return x * __builtin_amdgcn_rcpf(1.f + __builtin_amdgcn_exp2f(-1.4426950408889634f * x)); }
; template <int EPI>
; __device__ __forceinline__ void gemm_epi(const GemmArgs& G, const f32x4 (&a)[4][2], int rbase, int cbase, int fq, const float (&ssv)[4]) {
;     ...
;     const int row = rbase + m * 16;
;     float rs = 1.f;
;     if constexpr (EPI == EPI_GU || EPI == EPI_EVIN || EPI == EPI_ODIN) rs = rsqrtf(ssv[m] * (1.f / 2048.f) + 1e-6f);
;     if constexpr (EPI == EPI_GU) {
;       const f32x4 gv = a[m][0] * rs, uv = a[m][1] * rs;
;       const int hc = (cbase >> 1) + fq * 4;
;       u32x2 o = {cvtpk(silu_f(gv[0]) * uv[0], silu_f(gv[1]) * uv[1]), cvtpk(silu_f(gv[2]) * uv[2], silu_f(gv[3]) * uv[3])};
;       *reinterpret_cast<u32x2*>(G.d0 + (size_t)(row - G.row0) * DFF + hc) = o;
.LBB0_2558:
	v_readfirstlane_b32 s16, v224
	s_andn2_b32 s16, s16, 63
	s_nop 0
	v_add_u32_e32 v128, s16, v225
	s_nop 0
	v_and_b32_e32 v129, 15, v128
	v_ashrrev_i32_e32 v135, 2, v128
	v_and_or_b32 v129, v135, s85, v129
	v_lshrrev_b32_e32 v135, 1, v128
	v_and_b32_e32 v135, 0x60, v135
	v_or_b32_e32 v136, s29, v135
	v_lshrrev_b32_e32 v128, 2, v128
	v_ashrrev_i32_e32 v140, 1, v136
	v_and_b32_e32 v136, 12, v128
	s_waitcnt vmcnt(8)
	v_fmamk_f32 v128, v139, 0x3a000000, v229
	v_cmp_gt_f32_e32 vcc, s42, v128
	v_mul_f32_e32 v139, 0x4b800000, v128
	v_add_u32_e32 v144, s28, v129
	v_cndmask_b32_e32 v128, v128, v139, vcc
	v_rsq_f32_e32 v128, v128
	v_or_b32_e32 v140, v140, v136
	v_ashrrev_i32_e32 v141, 31, v140
	v_mul_f32_e32 v139, 0x45800000, v128
	v_cndmask_b32_e32 v128, v128, v139, vcc
	v_pk_mul_f32 v[120:121], v[128:129], v[120:121] op_sel_hi:[0,1]
	v_mul_f32_e32 v139, 0xbfb8aa3b, v120
	v_exp_f32_e32 v139, v139
	v_pk_mul_f32 v[124:125], v[128:129], v[124:125] op_sel_hi:[0,1]
	v_pk_mul_f32 v[122:123], v[128:129], v[122:123] op_sel_hi:[0,1]
	v_pk_mul_f32 v[126:127], v[128:129], v[126:127] op_sel_hi:[0,1]
	v_add_f32_e32 v139, 1.0, v139
	v_rcp_f32_e32 v139, v139
	v_pk_mul_f32 v[88:89], v[128:129], v[88:89] op_sel_hi:[0,1]
	v_pk_mul_f32 v[92:93], v[128:129], v[92:93] op_sel_hi:[0,1]
	v_pk_mul_f32 v[90:91], v[128:129], v[90:91] op_sel_hi:[0,1]
	v_mul_f32_e32 v120, v120, v139
	v_mul_f32_e32 v120, v124, v120
	v_mul_f32_e32 v124, 0xbfb8aa3b, v121
	v_exp_f32_e32 v124, v124
	v_pk_mul_f32 v[94:95], v[128:129], v[94:95] op_sel_hi:[0,1]
	v_add_f32_e32 v124, 1.0, v124
	v_rcp_f32_e32 v124, v124
	s_nop 0
	v_mul_f32_e32 v121, v121, v124
	v_mul_f32_e32 v121, v125, v121
	v_cvt_pk_bf16_f32 v142, v120, v121
	v_mul_f32_e32 v120, 0xbfb8aa3b, v122
	v_exp_f32_e32 v120, v120
	v_mul_f32_e32 v121, 0xbfb8aa3b, v123
	v_exp_f32_e32 v121, v121
	v_add_f32_e32 v120, 1.0, v120
	v_rcp_f32_e32 v120, v120
	v_add_f32_e32 v121, 1.0, v121
	v_rcp_f32_e32 v121, v121
	v_mul_f32_e32 v120, v122, v120
	v_mul_f32_e32 v120, v126, v120
	v_fmamk_f32 v126, v138, 0x3a000000, v229
	v_cmp_gt_f32_e32 vcc, s42, v126
	v_mul_f32_e32 v138, 0x4b800000, v126
	v_mul_f32_e32 v121, v123, v121
	v_cndmask_b32_e32 v126, v126, v138, vcc
	v_rsq_f32_e32 v126, v126
	v_mul_f32_e32 v121, v127, v121
	v_subrev_u32_e32 v127, s40, v144
	v_cvt_pk_bf16_f32 v143, v120, v121
	v_mul_f32_e32 v138, 0x45800000, v126
	v_cndmask_b32_e32 v126, v126, v138, vcc
	v_pk_mul_f32 v[112:113], v[126:127], v[112:113] op_sel_hi:[0,1]
	v_mul_f32_e32 v138, 0xbfb8aa3b, v112
	v_exp_f32_e32 v138, v138
	v_pk_mul_f32 v[116:117], v[126:127], v[116:117] op_sel_hi:[0,1]
	v_mov_b64_e32 v[120:121], s[10:11]
	v_mad_i64_i32 v[124:125], s[16:17], v127, s30, v[120:121]
	v_add_f32_e32 v138, 1.0, v138
	v_rcp_f32_e32 v138, v138
	v_lshlrev_b64 v[122:123], 1, v[140:141]
	v_lshl_add_u64 v[140:141], v[124:125], 0, v[122:123]
	v_pk_mul_f32 v[114:115], v[126:127], v[114:115] op_sel_hi:[0,1]
	v_mul_f32_e32 v112, v112, v138
	v_mul_f32_e32 v112, v116, v112
	v_mul_f32_e32 v116, 0xbfb8aa3b, v113
	v_exp_f32_e32 v116, v116
	global_store_dwordx2 v[140:141], v[142:143], off
	v_pk_mul_f32 v[118:119], v[126:127], v[118:119] op_sel_hi:[0,1]
	v_pk_mul_f32 v[80:81], v[126:127], v[80:81] op_sel_hi:[0,1]
	v_add_f32_e32 v116, 1.0, v116
	v_rcp_f32_e32 v116, v116
	v_pk_mul_f32 v[84:85], v[126:127], v[84:85] op_sel_hi:[0,1]
	v_pk_mul_f32 v[82:83], v[126:127], v[82:83] op_sel_hi:[0,1]
	v_pk_mul_f32 v[86:87], v[126:127], v[86:87] op_sel_hi:[0,1]
	v_mul_f32_e32 v113, v113, v116
	v_mul_f32_e32 v113, v117, v113
	v_cvt_pk_bf16_f32 v116, v112, v113
	v_mul_f32_e32 v112, 0xbfb8aa3b, v114
	v_exp_f32_e32 v112, v112
	v_mul_f32_e32 v113, 0xbfb8aa3b, v115
	v_exp_f32_e32 v113, v113
	v_add_f32_e32 v112, 1.0, v112
	v_rcp_f32_e32 v112, v112
	v_add_f32_e32 v113, 1.0, v113
	v_rcp_f32_e32 v113, v113
	v_mul_f32_e32 v112, v114, v112
	v_mul_f32_e32 v112, v118, v112
	v_mul_f32_e32 v113, v115, v113
	v_mul_f32_e32 v113, v119, v113
	v_cvt_pk_bf16_f32 v117, v112, v113
	v_or_b32_e32 v112, 16, v127
	v_mad_i64_i32 v[112:113], s[16:17], v112, s30, v[120:121]
	v_lshl_add_u64 v[114:115], v[112:113], 0, v[122:123]
	global_store_dwordx2 v[114:115], v[116:117], off
	v_fmamk_f32 v114, v137, 0x3a000000, v229
	v_cmp_gt_f32_e32 vcc, s42, v114
	v_mul_f32_e32 v115, 0x4b800000, v114
	s_nop 0
	v_cndmask_b32_e32 v114, v114, v115, vcc
	v_rsq_f32_e32 v114, v114
	s_nop 0
	v_mul_f32_e32 v115, 0x45800000, v114
	v_cndmask_b32_e32 v114, v114, v115, vcc
	v_pk_mul_f32 v[104:105], v[114:115], v[104:105] op_sel_hi:[0,1]
	v_pk_mul_f32 v[106:107], v[114:115], v[106:107] op_sel_hi:[0,1]
	v_pk_mul_f32 v[110:111], v[114:115], v[110:111] op_sel_hi:[0,1]
	v_pk_mul_f32 v[108:109], v[114:115], v[108:109] op_sel_hi:[0,1]
	v_mul_f32_e32 v115, 0xbfb8aa3b, v104
	v_exp_f32_e32 v115, v115
	s_nop 0
	v_add_f32_e32 v115, 1.0, v115
	v_rcp_f32_e32 v115, v115
	s_nop 0
	v_mul_f32_e32 v104, v104, v115
	v_mul_f32_e32 v104, v108, v104
	v_mul_f32_e32 v108, 0xbfb8aa3b, v105
	v_exp_f32_e32 v108, v108
	v_pk_mul_f32 v[72:73], v[114:115], v[72:73] op_sel_hi:[0,1]
	v_pk_mul_f32 v[76:77], v[114:115], v[76:77] op_sel_hi:[0,1]
	v_pk_mul_f32 v[74:75], v[114:115], v[74:75] op_sel_hi:[0,1]
	v_add_f32_e32 v108, 1.0, v108
	v_rcp_f32_e32 v108, v108
	v_pk_mul_f32 v[78:79], v[114:115], v[78:79] op_sel_hi:[0,1]
	v_mul_f32_e32 v105, v105, v108
	v_mul_f32_e32 v105, v109, v105
	v_cvt_pk_bf16_f32 v108, v104, v105
	v_mul_f32_e32 v104, 0xbfb8aa3b, v106
	v_exp_f32_e32 v104, v104
	v_mul_f32_e32 v105, 0xbfb8aa3b, v107
	v_exp_f32_e32 v105, v105
	v_add_f32_e32 v104, 1.0, v104
	v_rcp_f32_e32 v104, v104
	v_add_f32_e32 v105, 1.0, v105
	v_rcp_f32_e32 v105, v105
	v_mul_f32_e32 v104, v106, v104
; __device__ __forceinline__ float silu_f(float x) { return x * __builtin_amdgcn_rcpf(1.f + __builtin_amdgcn_exp2f(-1.4426950408889634f * x)); }
; template <int EPI>
; __device__ __forceinline__ void gemm_epi(const GemmArgs& G, const f32x4 (&a)[4][2], int rbase, int cbase, int fq, const float (&ssv)[4]) {
;     ...
;     if constexpr (EPI == EPI_GU) {
;       const f32x4 gv = a[m][0] * rs, uv = a[m][1] * rs;
;       const int hc = (cbase >> 1) + fq * 4;
;       u32x2 o = {cvtpk(silu_f(gv[0]) * uv[0], silu_f(gv[1]) * uv[1]), cvtpk(silu_f(gv[2]) * uv[2], silu_f(gv[3]) * uv[3])};
;       *reinterpret_cast<u32x2*>(G.d0 + (size_t)(row - G.row0) * DFF + hc) = o;
	v_mul_f32_e32 v104, v110, v104
	v_mul_f32_e32 v105, v107, v105
	v_mul_f32_e32 v105, v111, v105
	v_cvt_pk_bf16_f32 v109, v104, v105
	v_or_b32_e32 v104, 32, v127
	v_mad_i64_i32 v[104:105], s[16:17], v104, s30, v[120:121]
	v_lshl_add_u64 v[106:107], v[104:105], 0, v[122:123]
	global_store_dwordx2 v[106:107], v[108:109], off
	v_fmamk_f32 v106, v134, 0x3a000000, v229
	v_cmp_gt_f32_e32 vcc, s42, v106
	v_mul_f32_e32 v107, 0x4b800000, v106
	s_nop 0
	v_cndmask_b32_e32 v106, v106, v107, vcc
	v_rsq_f32_e32 v106, v106
	s_nop 0
	v_mul_f32_e32 v107, 0x45800000, v106
	v_cndmask_b32_e32 v106, v106, v107, vcc
	v_pk_mul_f32 v[96:97], v[106:107], v[96:97] op_sel_hi:[0,1]
	v_pk_mul_f32 v[98:99], v[106:107], v[98:99] op_sel_hi:[0,1]
	v_pk_mul_f32 v[102:103], v[106:107], v[102:103] op_sel_hi:[0,1]
	v_pk_mul_f32 v[100:101], v[106:107], v[100:101] op_sel_hi:[0,1]
	v_mul_f32_e32 v107, 0xbfb8aa3b, v96
	v_exp_f32_e32 v107, v107
	s_nop 0
	v_add_f32_e32 v107, 1.0, v107
	v_rcp_f32_e32 v107, v107
	s_nop 0
	v_mul_f32_e32 v96, v96, v107
	v_mul_f32_e32 v96, v100, v96
	v_mul_f32_e32 v100, 0xbfb8aa3b, v97
	v_exp_f32_e32 v100, v100
	v_pk_mul_f32 v[64:65], v[106:107], v[64:65] op_sel_hi:[0,1]
	v_pk_mul_f32 v[68:69], v[106:107], v[68:69] op_sel_hi:[0,1]
	v_pk_mul_f32 v[66:67], v[106:107], v[66:67] op_sel_hi:[0,1]
	v_add_f32_e32 v100, 1.0, v100
	v_rcp_f32_e32 v100, v100
	v_pk_mul_f32 v[70:71], v[106:107], v[70:71] op_sel_hi:[0,1]
	v_mul_f32_e32 v97, v97, v100
	v_mul_f32_e32 v97, v101, v97
	v_cvt_pk_bf16_f32 v100, v96, v97
	v_mul_f32_e32 v96, 0xbfb8aa3b, v98
	v_exp_f32_e32 v96, v96
	v_mul_f32_e32 v97, 0xbfb8aa3b, v99
	v_exp_f32_e32 v97, v97
	v_add_f32_e32 v96, 1.0, v96
	v_rcp_f32_e32 v96, v96
	v_add_f32_e32 v97, 1.0, v97
	v_rcp_f32_e32 v97, v97
	v_mul_f32_e32 v96, v98, v96
	v_mul_f32_e32 v96, v102, v96
	v_mul_f32_e32 v97, v99, v97
	v_mul_f32_e32 v97, v103, v97
	v_cvt_pk_bf16_f32 v101, v96, v97
	v_or_b32_e32 v96, 48, v127
	v_mad_i64_i32 v[96:97], s[16:17], v96, s30, v[120:121]
	v_lshl_add_u64 v[98:99], v[96:97], 0, v[122:123]
	global_store_dwordx2 v[98:99], v[100:101], off
	v_mul_f32_e32 v100, 0xbfb8aa3b, v88
	v_exp_f32_e32 v100, v100
	v_or_b32_e32 v98, s20, v135
	v_ashrrev_i32_e32 v98, 1, v98
	v_or_b32_e32 v98, v98, v136
	v_add_f32_e32 v100, 1.0, v100
	v_rcp_f32_e32 v100, v100
	v_ashrrev_i32_e32 v99, 31, v98
	v_mul_f32_e32 v88, v88, v100
	v_mul_f32_e32 v88, v92, v88
	v_mul_f32_e32 v92, 0xbfb8aa3b, v89
	v_exp_f32_e32 v92, v92
	s_nop 0
	v_add_f32_e32 v92, 1.0, v92
	v_rcp_f32_e32 v92, v92
	s_nop 0
	v_mul_f32_e32 v89, v89, v92
	v_mul_f32_e32 v89, v93, v89
	v_cvt_pk_bf16_f32 v92, v88, v89
	v_mul_f32_e32 v88, 0xbfb8aa3b, v90
	v_mul_f32_e32 v89, 0xbfb8aa3b, v91
	v_exp_f32_e32 v88, v88
	v_exp_f32_e32 v89, v89
	v_add_f32_e32 v88, 1.0, v88
	v_add_f32_e32 v89, 1.0, v89
	v_rcp_f32_e32 v88, v88
	v_rcp_f32_e32 v89, v89
	v_mul_f32_e32 v88, v90, v88
	v_mul_f32_e32 v89, v91, v89
	v_mul_f32_e32 v88, v94, v88
	v_mul_f32_e32 v89, v95, v89
	v_cvt_pk_bf16_f32 v93, v88, v89
	v_lshlrev_b64 v[88:89], 1, v[98:99]
	v_lshl_add_u64 v[90:91], v[124:125], 0, v[88:89]
	global_store_dwordx2 v[90:91], v[92:93], off
	v_mul_f32_e32 v90, 0xbfb8aa3b, v80
	v_exp_f32_e32 v90, v90
	s_nop 0
	v_add_f32_e32 v90, 1.0, v90
	v_rcp_f32_e32 v90, v90
	s_nop 0
	v_mul_f32_e32 v80, v80, v90
	v_mul_f32_e32 v80, v84, v80
	v_mul_f32_e32 v84, 0xbfb8aa3b, v81
	v_exp_f32_e32 v84, v84
	s_nop 0
	v_add_f32_e32 v84, 1.0, v84
	v_rcp_f32_e32 v84, v84
	s_nop 0
	v_mul_f32_e32 v81, v81, v84
	v_mul_f32_e32 v81, v85, v81
	v_cvt_pk_bf16_f32 v80, v80, v81
	v_mul_f32_e32 v81, 0xbfb8aa3b, v82
	v_exp_f32_e32 v81, v81
	s_nop 0
	v_add_f32_e32 v81, 1.0, v81
	v_rcp_f32_e32 v81, v81
	s_nop 0
	v_mul_f32_e32 v81, v82, v81
	v_mul_f32_e32 v82, 0xbfb8aa3b, v83
	v_exp_f32_e32 v82, v82
	v_mul_f32_e32 v81, v86, v81
	v_add_f32_e32 v82, 1.0, v82
	v_rcp_f32_e32 v82, v82
	s_nop 0
	v_mul_f32_e32 v82, v83, v82
	v_mul_f32_e32 v82, v87, v82
	v_cvt_pk_bf16_f32 v81, v81, v82
	v_lshl_add_u64 v[82:83], v[112:113], 0, v[88:89]
	global_store_dwordx2 v[82:83], v[80:81], off
	v_mul_f32_e32 v80, 0xbfb8aa3b, v72
	v_exp_f32_e32 v80, v80
	s_nop 0
	v_add_f32_e32 v80, 1.0, v80
	v_rcp_f32_e32 v80, v80
	s_nop 0
	v_mul_f32_e32 v72, v72, v80
	v_mul_f32_e32 v72, v76, v72
	v_mul_f32_e32 v76, 0xbfb8aa3b, v73
	v_exp_f32_e32 v76, v76
	s_nop 0
	v_add_f32_e32 v76, 1.0, v76
	v_rcp_f32_e32 v76, v76
	s_nop 0
	v_mul_f32_e32 v73, v73, v76
	v_mul_f32_e32 v73, v77, v73
	v_cvt_pk_bf16_f32 v72, v72, v73
	v_mul_f32_e32 v73, 0xbfb8aa3b, v74
	v_exp_f32_e32 v73, v73
	s_nop 0
	v_add_f32_e32 v73, 1.0, v73
	v_rcp_f32_e32 v73, v73
	s_nop 0
	v_mul_f32_e32 v73, v74, v73
	v_mul_f32_e32 v74, 0xbfb8aa3b, v75
	v_exp_f32_e32 v74, v74
	v_mul_f32_e32 v73, v78, v73
	v_add_f32_e32 v74, 1.0, v74
	v_rcp_f32_e32 v74, v74
	s_nop 0
	v_mul_f32_e32 v74, v75, v74
	v_mul_f32_e32 v74, v79, v74
	v_cvt_pk_bf16_f32 v73, v73, v74
	v_lshl_add_u64 v[74:75], v[104:105], 0, v[88:89]
	global_store_dwordx2 v[74:75], v[72:73], off
	v_mul_f32_e32 v72, 0xbfb8aa3b, v64
	v_exp_f32_e32 v72, v72
	s_nop 0
	v_add_f32_e32 v72, 1.0, v72
	v_rcp_f32_e32 v72, v72
	s_nop 0
	v_mul_f32_e32 v64, v64, v72
	v_mul_f32_e32 v64, v68, v64
	v_mul_f32_e32 v68, 0xbfb8aa3b, v65
	v_exp_f32_e32 v68, v68
	s_nop 0
	v_add_f32_e32 v68, 1.0, v68
	v_rcp_f32_e32 v68, v68
	s_nop 0
	v_mul_f32_e32 v65, v65, v68
	v_mul_f32_e32 v65, v69, v65
	v_cvt_pk_bf16_f32 v64, v64, v65
	v_mul_f32_e32 v65, 0xbfb8aa3b, v66
	v_exp_f32_e32 v65, v65
	s_nop 0
	v_add_f32_e32 v65, 1.0, v65
	v_rcp_f32_e32 v65, v65
	s_nop 0
	v_mul_f32_e32 v65, v66, v65
	v_mul_f32_e32 v66, 0xbfb8aa3b, v67
	v_exp_f32_e32 v66, v66
	v_mul_f32_e32 v65, v70, v65
	v_add_f32_e32 v66, 1.0, v66
	v_rcp_f32_e32 v66, v66
	s_nop 0
; __device__ __forceinline__ float silu_f(float x) { return x * __builtin_amdgcn_rcpf(1.f + __builtin_amdgcn_exp2f(-1.4426950408889634f * x)); }
; template <int EPI>
; __device__ __forceinline__ void gemm_epi(const GemmArgs& G, const f32x4 (&a)[4][2], int rbase, int cbase, int fq, const float (&ssv)[4]) {
;     ...
;     const int row = rbase + m * 16;
;     float rs = 1.f;
;     if constexpr (EPI == EPI_GU || EPI == EPI_EVIN || EPI == EPI_ODIN) rs = rsqrtf(ssv[m] * (1.f / 2048.f) + 1e-6f);
;     if constexpr (EPI == EPI_GU) {
;       const f32x4 gv = a[m][0] * rs, uv = a[m][1] * rs;
;       const int hc = (cbase >> 1) + fq * 4;
;       u32x2 o = {cvtpk(silu_f(gv[0]) * uv[0], silu_f(gv[1]) * uv[1]), cvtpk(silu_f(gv[2]) * uv[2], silu_f(gv[3]) * uv[3])};
;       *reinterpret_cast<u32x2*>(G.d0 + (size_t)(row - G.row0) * DFF + hc) = o;
	v_mul_f32_e32 v66, v67, v66
	v_mul_f32_e32 v66, v71, v66
	v_cvt_pk_bf16_f32 v65, v65, v66
	v_lshl_add_u64 v[66:67], v[96:97], 0, v[88:89]
	global_store_dwordx2 v[66:67], v[64:65], off
	v_fmamk_f32 v64, v133, 0x3a000000, v229
	v_cmp_gt_f32_e32 vcc, s42, v64
	v_mul_f32_e32 v66, 0x4b800000, v64
	v_add_u32_e32 v65, s21, v129
	v_cndmask_b32_e32 v64, v64, v66, vcc
	v_rsq_f32_e32 v64, v64
	s_nop 0
	v_mul_f32_e32 v66, 0x45800000, v64
	v_cndmask_b32_e32 v64, v64, v66, vcc
	v_pk_mul_f32 v[56:57], v[64:65], v[56:57] op_sel_hi:[0,1]
	v_mul_f32_e32 v66, 0xbfb8aa3b, v56
	v_exp_f32_e32 v66, v66
	v_pk_mul_f32 v[60:61], v[64:65], v[60:61] op_sel_hi:[0,1]
	v_pk_mul_f32 v[58:59], v[64:65], v[58:59] op_sel_hi:[0,1]
	v_pk_mul_f32 v[62:63], v[64:65], v[62:63] op_sel_hi:[0,1]
	v_add_f32_e32 v66, 1.0, v66
	v_rcp_f32_e32 v66, v66
	v_pk_mul_f32 v[24:25], v[64:65], v[24:25] op_sel_hi:[0,1]
	v_pk_mul_f32 v[28:29], v[64:65], v[28:29] op_sel_hi:[0,1]
	v_pk_mul_f32 v[26:27], v[64:65], v[26:27] op_sel_hi:[0,1]
	v_mul_f32_e32 v56, v56, v66
	v_mul_f32_e32 v56, v60, v56
	v_mul_f32_e32 v60, 0xbfb8aa3b, v57
	v_exp_f32_e32 v60, v60
	v_pk_mul_f32 v[30:31], v[64:65], v[30:31] op_sel_hi:[0,1]
	v_add_f32_e32 v60, 1.0, v60
	v_rcp_f32_e32 v60, v60
	s_nop 0
	v_mul_f32_e32 v57, v57, v60
	v_mul_f32_e32 v57, v61, v57
	v_cvt_pk_bf16_f32 v60, v56, v57
	v_mul_f32_e32 v56, 0xbfb8aa3b, v58
	v_mul_f32_e32 v57, 0xbfb8aa3b, v59
	v_exp_f32_e32 v56, v56
	v_exp_f32_e32 v57, v57
	v_add_f32_e32 v56, 1.0, v56
	v_add_f32_e32 v57, 1.0, v57
	v_rcp_f32_e32 v56, v56
	v_rcp_f32_e32 v57, v57
	v_mul_f32_e32 v56, v58, v56
	v_mul_f32_e32 v57, v59, v57
	v_mul_f32_e32 v56, v62, v56
	v_mul_f32_e32 v57, v63, v57
	v_subrev_u32_e32 v59, s40, v65
	v_cvt_pk_bf16_f32 v61, v56, v57
	v_mad_i64_i32 v[56:57], s[16:17], v59, s30, v[120:121]
	v_lshl_add_u64 v[62:63], v[56:57], 0, v[122:123]
	v_fmamk_f32 v58, v132, 0x3a000000, v229
	global_store_dwordx2 v[62:63], v[60:61], off
	v_cmp_gt_f32_e32 vcc, s42, v58
	v_mul_f32_e32 v60, 0x4b800000, v58
	s_nop 0
	v_cndmask_b32_e32 v58, v58, v60, vcc
	v_rsq_f32_e32 v58, v58
	s_nop 0
	v_mul_f32_e32 v60, 0x45800000, v58
	v_cndmask_b32_e32 v58, v58, v60, vcc
	v_pk_mul_f32 v[48:49], v[58:59], v[48:49] op_sel_hi:[0,1]
	v_mul_f32_e32 v60, 0xbfb8aa3b, v48
	v_exp_f32_e32 v60, v60
	v_pk_mul_f32 v[52:53], v[58:59], v[52:53] op_sel_hi:[0,1]
	v_pk_mul_f32 v[50:51], v[58:59], v[50:51] op_sel_hi:[0,1]
	v_pk_mul_f32 v[54:55], v[58:59], v[54:55] op_sel_hi:[0,1]
	v_add_f32_e32 v60, 1.0, v60
	v_rcp_f32_e32 v60, v60
	v_pk_mul_f32 v[16:17], v[58:59], v[16:17] op_sel_hi:[0,1]
	v_pk_mul_f32 v[20:21], v[58:59], v[20:21] op_sel_hi:[0,1]
	v_pk_mul_f32 v[18:19], v[58:59], v[18:19] op_sel_hi:[0,1]
	v_mul_f32_e32 v48, v48, v60
	v_mul_f32_e32 v48, v52, v48
	v_mul_f32_e32 v52, 0xbfb8aa3b, v49
	v_exp_f32_e32 v52, v52
	v_pk_mul_f32 v[22:23], v[58:59], v[22:23] op_sel_hi:[0,1]
	v_add_f32_e32 v52, 1.0, v52
	v_rcp_f32_e32 v52, v52
	s_nop 0
	v_mul_f32_e32 v49, v49, v52
	v_mul_f32_e32 v49, v53, v49
	v_cvt_pk_bf16_f32 v52, v48, v49
	v_mul_f32_e32 v48, 0xbfb8aa3b, v50
	v_exp_f32_e32 v48, v48
	v_mul_f32_e32 v49, 0xbfb8aa3b, v51
	v_exp_f32_e32 v49, v49
	v_add_f32_e32 v48, 1.0, v48
	v_rcp_f32_e32 v48, v48
	v_add_f32_e32 v49, 1.0, v49
	v_rcp_f32_e32 v49, v49
	v_mul_f32_e32 v48, v50, v48
	v_mul_f32_e32 v48, v54, v48
	v_mul_f32_e32 v49, v51, v49
	v_mul_f32_e32 v49, v55, v49
	v_cvt_pk_bf16_f32 v53, v48, v49
	v_or_b32_e32 v48, 16, v59
	v_mad_i64_i32 v[48:49], s[16:17], v48, s30, v[120:121]
	v_lshl_add_u64 v[50:51], v[48:49], 0, v[122:123]
	global_store_dwordx2 v[50:51], v[52:53], off
	v_fmamk_f32 v50, v131, 0x3a000000, v229
	v_cmp_gt_f32_e32 vcc, s42, v50
	v_mul_f32_e32 v51, 0x4b800000, v50
	s_nop 0
	v_cndmask_b32_e32 v50, v50, v51, vcc
	v_rsq_f32_e32 v50, v50
	s_nop 0
	v_mul_f32_e32 v51, 0x45800000, v50
	v_cndmask_b32_e32 v50, v50, v51, vcc
	v_pk_mul_f32 v[40:41], v[50:51], v[40:41] op_sel_hi:[0,1]
	v_pk_mul_f32 v[42:43], v[50:51], v[42:43] op_sel_hi:[0,1]
	v_pk_mul_f32 v[46:47], v[50:51], v[46:47] op_sel_hi:[0,1]
	v_pk_mul_f32 v[44:45], v[50:51], v[44:45] op_sel_hi:[0,1]
	v_mul_f32_e32 v51, 0xbfb8aa3b, v40
	v_exp_f32_e32 v51, v51
	s_nop 0
	v_add_f32_e32 v51, 1.0, v51
	v_rcp_f32_e32 v51, v51
	s_nop 0
	v_mul_f32_e32 v40, v40, v51
	v_mul_f32_e32 v40, v44, v40
	v_mul_f32_e32 v44, 0xbfb8aa3b, v41
	v_exp_f32_e32 v44, v44
	v_pk_mul_f32 v[8:9], v[50:51], v[8:9] op_sel_hi:[0,1]
	v_pk_mul_f32 v[12:13], v[50:51], v[12:13] op_sel_hi:[0,1]
	v_pk_mul_f32 v[10:11], v[50:51], v[10:11] op_sel_hi:[0,1]
	v_add_f32_e32 v44, 1.0, v44
	v_rcp_f32_e32 v44, v44
	v_pk_mul_f32 v[14:15], v[50:51], v[14:15] op_sel_hi:[0,1]
	v_mul_f32_e32 v41, v41, v44
	v_mul_f32_e32 v41, v45, v41
	v_cvt_pk_bf16_f32 v44, v40, v41
	v_mul_f32_e32 v40, 0xbfb8aa3b, v42
	v_exp_f32_e32 v40, v40
	v_mul_f32_e32 v41, 0xbfb8aa3b, v43
	v_exp_f32_e32 v41, v41
	v_add_f32_e32 v40, 1.0, v40
	v_rcp_f32_e32 v40, v40
	v_add_f32_e32 v41, 1.0, v41
	v_rcp_f32_e32 v41, v41
	v_mul_f32_e32 v40, v42, v40
	v_mul_f32_e32 v40, v46, v40
	v_mul_f32_e32 v41, v43, v41
	v_mul_f32_e32 v41, v47, v41
	v_cvt_pk_bf16_f32 v45, v40, v41
	v_or_b32_e32 v40, 32, v59
	v_mad_i64_i32 v[40:41], s[16:17], v40, s30, v[120:121]
	v_lshl_add_u64 v[42:43], v[40:41], 0, v[122:123]
	global_store_dwordx2 v[42:43], v[44:45], off
	v_fmamk_f32 v42, v130, 0x3a000000, v229
; __device__ __forceinline__ float silu_f(float x) { return x * __builtin_amdgcn_rcpf(1.f + __builtin_amdgcn_exp2f(-1.4426950408889634f * x)); }
; template <int EPI>
; __device__ __forceinline__ void gemm_epi(const GemmArgs& G, const f32x4 (&a)[4][2], int rbase, int cbase, int fq, const float (&ssv)[4]) {
;     ...
;     if constexpr (EPI == EPI_GU) {
;       const f32x4 gv = a[m][0] * rs, uv = a[m][1] * rs;
;       const int hc = (cbase >> 1) + fq * 4;
;       u32x2 o = {cvtpk(silu_f(gv[0]) * uv[0], silu_f(gv[1]) * uv[1]), cvtpk(silu_f(gv[2]) * uv[2], silu_f(gv[3]) * uv[3])};
;       *reinterpret_cast<u32x2*>(G.d0 + (size_t)(row - G.row0) * DFF + hc) = o;
; template <int EPI>
; __device__ __forceinline__ void gemm_phase(const GemmArgs& G, char* shm) {
;     ...
;   for (int t = vb; t < nwg; t += gridDim.x) {
;     int brow, bcol, nbrow = 0, nbcol = 0; gemm_map_tile(G, t, brow, bcol);
;     const bool has_next = t + (int)gridDim.x < nwg;
;     if (has_next) gemm_map_tile(G, t + gridDim.x, nbrow, nbcol);
;     gemm_tile<EPI>(G, brow, bcol, shm, t == vb, has_next, nbrow, nbcol);
	v_cmp_gt_f32_e32 vcc, s42, v42
	v_mul_f32_e32 v43, 0x4b800000, v42
	s_nop 0
	v_cndmask_b32_e32 v42, v42, v43, vcc
	v_rsq_f32_e32 v42, v42
	s_nop 0
	v_mul_f32_e32 v43, 0x45800000, v42
	v_cndmask_b32_e32 v42, v42, v43, vcc
	v_pk_mul_f32 v[32:33], v[42:43], v[32:33] op_sel_hi:[0,1]
	v_pk_mul_f32 v[34:35], v[42:43], v[34:35] op_sel_hi:[0,1]
	v_pk_mul_f32 v[38:39], v[42:43], v[38:39] op_sel_hi:[0,1]
	v_pk_mul_f32 v[36:37], v[42:43], v[36:37] op_sel_hi:[0,1]
	v_mul_f32_e32 v43, 0xbfb8aa3b, v32
	v_exp_f32_e32 v43, v43
	s_nop 0
	v_add_f32_e32 v43, 1.0, v43
	v_rcp_f32_e32 v43, v43
	s_nop 0
	v_mul_f32_e32 v32, v32, v43
	v_mul_f32_e32 v32, v36, v32
	v_mul_f32_e32 v36, 0xbfb8aa3b, v33
	v_exp_f32_e32 v36, v36
	v_pk_mul_f32 v[0:1], v[42:43], v[0:1] op_sel_hi:[0,1]
	v_pk_mul_f32 v[4:5], v[42:43], v[4:5] op_sel_hi:[0,1]
	v_pk_mul_f32 v[2:3], v[42:43], v[2:3] op_sel_hi:[0,1]
	v_add_f32_e32 v36, 1.0, v36
	v_rcp_f32_e32 v36, v36
	v_pk_mul_f32 v[6:7], v[42:43], v[6:7] op_sel_hi:[0,1]
	v_mul_f32_e32 v33, v33, v36
	v_mul_f32_e32 v33, v37, v33
	v_cvt_pk_bf16_f32 v36, v32, v33
	v_mul_f32_e32 v32, 0xbfb8aa3b, v34
	v_exp_f32_e32 v32, v32
	v_mul_f32_e32 v33, 0xbfb8aa3b, v35
	v_exp_f32_e32 v33, v33
	v_add_f32_e32 v32, 1.0, v32
	v_rcp_f32_e32 v32, v32
	v_add_f32_e32 v33, 1.0, v33
	v_rcp_f32_e32 v33, v33
	v_mul_f32_e32 v32, v34, v32
	v_mul_f32_e32 v32, v38, v32
	v_mul_f32_e32 v33, v35, v33
	v_mul_f32_e32 v33, v39, v33
	v_cvt_pk_bf16_f32 v37, v32, v33
	v_or_b32_e32 v32, 48, v59
	v_mad_i64_i32 v[32:33], s[16:17], v32, s30, v[120:121]
	v_lshl_add_u64 v[34:35], v[32:33], 0, v[122:123]
	global_store_dwordx2 v[34:35], v[36:37], off
	v_mul_f32_e32 v34, 0xbfb8aa3b, v24
	v_exp_f32_e32 v34, v34
	s_nop 0
	v_add_f32_e32 v34, 1.0, v34
	v_rcp_f32_e32 v34, v34
	s_nop 0
	v_mul_f32_e32 v24, v24, v34
	v_mul_f32_e32 v24, v28, v24
	v_mul_f32_e32 v28, 0xbfb8aa3b, v25
	v_exp_f32_e32 v28, v28
	s_nop 0
	v_add_f32_e32 v28, 1.0, v28
	v_rcp_f32_e32 v28, v28
	s_nop 0
	v_mul_f32_e32 v25, v25, v28
	v_mul_f32_e32 v25, v29, v25
	v_cvt_pk_bf16_f32 v24, v24, v25
	v_mul_f32_e32 v25, 0xbfb8aa3b, v26
	v_exp_f32_e32 v25, v25
	s_nop 0
	v_add_f32_e32 v25, 1.0, v25
	v_rcp_f32_e32 v25, v25
	s_nop 0
	v_mul_f32_e32 v25, v26, v25
	v_mul_f32_e32 v26, 0xbfb8aa3b, v27
	v_exp_f32_e32 v26, v26
	v_mul_f32_e32 v25, v30, v25
	v_add_f32_e32 v26, 1.0, v26
	v_rcp_f32_e32 v26, v26
	s_nop 0
	v_mul_f32_e32 v26, v27, v26
	v_mul_f32_e32 v26, v31, v26
	v_cvt_pk_bf16_f32 v25, v25, v26
	v_lshl_add_u64 v[26:27], v[56:57], 0, v[88:89]
	global_store_dwordx2 v[26:27], v[24:25], off
	v_mul_f32_e32 v24, 0xbfb8aa3b, v16
	v_exp_f32_e32 v24, v24
	s_nop 0
	v_add_f32_e32 v24, 1.0, v24
	v_rcp_f32_e32 v24, v24
	s_nop 0
	v_mul_f32_e32 v16, v16, v24
	v_mul_f32_e32 v16, v20, v16
	v_mul_f32_e32 v20, 0xbfb8aa3b, v17
	v_exp_f32_e32 v20, v20
	s_nop 0
	v_add_f32_e32 v20, 1.0, v20
	v_rcp_f32_e32 v20, v20
	s_nop 0
	v_mul_f32_e32 v17, v17, v20
	v_mul_f32_e32 v17, v21, v17
	v_cvt_pk_bf16_f32 v16, v16, v17
	v_mul_f32_e32 v17, 0xbfb8aa3b, v18
	v_exp_f32_e32 v17, v17
	s_nop 0
	v_add_f32_e32 v17, 1.0, v17
	v_rcp_f32_e32 v17, v17
	s_nop 0
	v_mul_f32_e32 v17, v18, v17
	v_mul_f32_e32 v18, 0xbfb8aa3b, v19
	v_exp_f32_e32 v18, v18
	v_mul_f32_e32 v17, v22, v17
	v_add_f32_e32 v18, 1.0, v18
	v_rcp_f32_e32 v18, v18
	s_nop 0
	v_mul_f32_e32 v18, v19, v18
	v_mul_f32_e32 v18, v23, v18
	v_cvt_pk_bf16_f32 v17, v17, v18
	v_lshl_add_u64 v[18:19], v[48:49], 0, v[88:89]
	global_store_dwordx2 v[18:19], v[16:17], off
	v_mul_f32_e32 v16, 0xbfb8aa3b, v8
	v_exp_f32_e32 v16, v16
	s_nop 0
	v_add_f32_e32 v16, 1.0, v16
	v_rcp_f32_e32 v16, v16
	s_nop 0
	v_mul_f32_e32 v8, v8, v16
	v_mul_f32_e32 v8, v12, v8
	v_mul_f32_e32 v12, 0xbfb8aa3b, v9
	v_exp_f32_e32 v12, v12
	s_nop 0
	v_add_f32_e32 v12, 1.0, v12
	v_rcp_f32_e32 v12, v12
	s_nop 0
	v_mul_f32_e32 v9, v9, v12
	v_mul_f32_e32 v9, v13, v9
	v_cvt_pk_bf16_f32 v8, v8, v9
	v_mul_f32_e32 v9, 0xbfb8aa3b, v10
	v_exp_f32_e32 v9, v9
	s_nop 0
	v_add_f32_e32 v9, 1.0, v9
	v_rcp_f32_e32 v9, v9
	s_nop 0
	v_mul_f32_e32 v9, v10, v9
	v_mul_f32_e32 v10, 0xbfb8aa3b, v11
	v_exp_f32_e32 v10, v10
	v_mul_f32_e32 v9, v14, v9
	v_add_f32_e32 v10, 1.0, v10
	v_rcp_f32_e32 v10, v10
	s_nop 0
	v_mul_f32_e32 v10, v11, v10
	v_mul_f32_e32 v10, v15, v10
	v_cvt_pk_bf16_f32 v9, v9, v10
	v_lshl_add_u64 v[10:11], v[40:41], 0, v[88:89]
	global_store_dwordx2 v[10:11], v[8:9], off
	v_mul_f32_e32 v8, 0xbfb8aa3b, v0
	v_exp_f32_e32 v8, v8
	s_nop 0
	v_add_f32_e32 v8, 1.0, v8
	v_rcp_f32_e32 v8, v8
	s_nop 0
	v_mul_f32_e32 v0, v0, v8
	v_mul_f32_e32 v0, v4, v0
	v_mul_f32_e32 v4, 0xbfb8aa3b, v1
	v_exp_f32_e32 v4, v4
	s_nop 0
	v_add_f32_e32 v4, 1.0, v4
	v_rcp_f32_e32 v4, v4
	s_nop 0
	v_mul_f32_e32 v1, v1, v4
	v_mul_f32_e32 v1, v5, v1
	v_cvt_pk_bf16_f32 v0, v0, v1
	v_mul_f32_e32 v1, 0xbfb8aa3b, v2
	v_exp_f32_e32 v1, v1
	s_nop 0
	v_add_f32_e32 v1, 1.0, v1
	v_rcp_f32_e32 v1, v1
	s_nop 0
	v_mul_f32_e32 v1, v2, v1
	v_mul_f32_e32 v2, 0xbfb8aa3b, v3
	v_exp_f32_e32 v2, v2
	v_mul_f32_e32 v1, v6, v1
	v_add_f32_e32 v2, 1.0, v2
	v_rcp_f32_e32 v2, v2
	s_nop 0
	v_mul_f32_e32 v2, v3, v2
	v_mul_f32_e32 v2, v7, v2
	v_cvt_pk_bf16_f32 v1, v1, v2
	v_lshl_add_u64 v[2:3], v[32:33], 0, v[88:89]
	global_store_dwordx2 v[2:3], v[0:1], off
	s_andn2_b64 vcc, exec, s[14:15]
	s_mov_b32 s18, s25
	s_cbranch_vccz .LBB0_2571

; #define STAGE_A(P, br, kt) do { const char* _base = (const char*)(((kt) < G.ksplit ? G.A1 : A2m) + (long)(br) * G.lda + (long)(kt) * BK); \
;     __builtin_amdgcn_global_load_lds((const unsigned*)(_base + aoff0), (unsigned*)((char*)(P) + sb0), 16, 0, 0); \
;     __builtin_amdgcn_global_load_lds((const unsigned*)(_base + aoff1), (unsigned*)((char*)(P) + sb1), 16, 0, 0); } while (0)
; #define STAGE_B(P, br, kt) do { const char* _base = (const char*)(G.Bt + (long)(br) * G.ldb + (long)(kt) * BK); \
;     __builtin_amdgcn_global_load_lds((const unsigned*)(_base + boff0), (unsigned*)((char*)(P) + sb0), 16, 0, 0); \
;     __builtin_amdgcn_global_load_lds((const unsigned*)(_base + boff1), (unsigned*)((char*)(P) + sb1), 16, 0, 0); } while (0)
;     ...
;   const int K = G.K;
;   const u16* A2m = G.A2 - (long)G.ksplit * BK;
;   int t1 = otid();
;   const int wid = t1 >> 6, lane = t1 & 63, wr = wid >> 2, wc = wid & 3, fr = lane & 15, fq = lane >> 4;
;   const int sb0 = t1 * 16, sb1 = sb0 + 8192;
;   const int swz_ = lds_byte(fr, fq * 8);
;   const char* a_rd = shmc + wr * 8192 + swz_;
;   const char* b_rd = shmc + 4 * (HT * 2) + wc * 4096 + swz_;
;   int r0_, c0_, r1_, c1_; stage_rc(sb0, r0_, c0_); stage_rc(sb1, r1_, c1_);
;   const unsigned aoff0 = (unsigned)(r0_ * G.lda + c0_) * 2u, aoff1 = (unsigned)(r1_ * G.lda + c1_) * 2u;
;   const unsigned boff0 = (unsigned)(r0_ * G.ldb + c0_) * 2u, boff1 = (unsigned)(r1_ * G.ldb + c1_) * 2u;
;   f32x4 acc[2][2][4][2] = {};
;   bf16x8 At[4][2], B0[2][2], B1[2][2];
;   const int nt = K / BK;
;   if (EPI == EPI_RESID || first) {
;     STAGE_B(SB(0, 0), bcol, 0); STAGE_A(SA(0, 0), brow, 0);
;     STAGE_B(SB(0, 1), bcol + HALF, 0); STAGE_A(SA(0, 1), brow + HALF, 0);
;   }
.LBB0_2561:
	s_ashr_i32 s19, s18, 31
	s_lshr_b32 s19, s19, 29
	s_add_i32 s19, s18, s19
	s_ashr_i32 s20, s19, 3
	s_and_b32 s19, s19, -8
	s_sub_i32 s19, s18, s19
	s_cmp_lt_i32 s19, 0
	s_cselect_b32 s21, s43, 0x2c0
	s_mul_i32 s19, s19, s21
	s_add_i32 s19, s19, s20
	s_mul_hi_i32 s20, s19, 0x2e8ba2e9
	s_lshr_b32 s21, s20, 31
	s_ashr_i32 s20, s20, 6
	s_add_i32 s20, s20, s21
	s_mul_i32 s21, s20, 0x160
	s_sub_i32 s19, s19, s21
	s_sext_i32_i16 s21, s19
	s_bfe_u32 s21, s21, 0x3001c
	s_add_i32 s21, s19, s21
	s_sext_i32_i16 s28, s21
	s_and_b32 s21, s21, 0xfff8
	s_sub_i32 s19, s19, s21
	s_sext_i32_i16 s19, s19
	s_lshl_b32 s20, s20, 11
	s_ashr_i32 s29, s28, 3
	s_lshl_b32 s19, s19, 8
	s_add_i32 s28, s20, s40
	s_add_i32 s28, s28, s19
	v_readfirstlane_b32 s19, v224
	s_andn2_b32 s19, s19, 63
	s_cmp_lg_u32 s18, s22
	v_add_u32_e32 v144, s19, v225
	v_readlane_b32 s19, v253, 45
	v_bfe_i32 v1, v144, 27, 1
	v_lshlrev_b32_e32 v148, 4, v144
	v_lshrrev_b32_e32 v1, 22, v1
	v_add_u32_e32 v1, v148, v1
	v_and_b32_e32 v1, 0xfffffc00, v1
	v_sub_u32_e32 v1, v148, v1
	v_lshrrev_b32_e32 v2, 4, v1
	v_bitop3_b32 v3, v2, v1, 32 bitop3:0x6c
	v_ashrrev_i32_e32 v1, 31, v1
	v_lshrrev_b32_e32 v1, 26, v1
	v_add_u32_e32 v1, v3, v1
	v_ashrrev_i32_e32 v1, 6, v1
	v_add_u32_e32 v5, 0x2000, v148
	v_mul_i32_i24_e32 v4, 64, v1
	v_sub_u32_e32 v3, v3, v4
	v_ashrrev_i32_e32 v4, 31, v5
	v_lshrrev_b32_e32 v4, 22, v4
	v_add_u32_e32 v4, v5, v4
	v_ashrrev_i32_e32 v4, 10, v4
	v_ashrrev_i32_e32 v0, 31, v144
	v_mul_i32_i24_e32 v6, 0x400, v4
	v_lshrrev_b32_e32 v0, 26, v0
	v_sub_u32_e32 v5, v5, v6
	v_add_u32_e32 v0, v144, v0
	v_lshrrev_b32_e32 v6, 4, v5
	v_ashrrev_i32_e32 v0, 6, v0
	v_bitop3_b32 v7, v6, v5, 32 bitop3:0x6c
	v_lshlrev_b32_e32 v5, 3, v4
	v_lshlrev_b32_e32 v2, 3, v0
	v_and_b32_e32 v6, 0x3fffff0, v5
	v_ashrrev_i32_e32 v5, 31, v7
	v_and_b32_e32 v2, 0x3fffff0, v2
	v_lshrrev_b32_e32 v5, 26, v5
	s_waitcnt vmcnt(16)
	v_add_u32_e32 v8, v1, v2
	v_lshlrev_b32_e32 v2, 5, v0
	v_add_u32_e32 v9, v7, v5
	v_and_b32_e32 v2, 32, v2
	v_ashrrev_i16_sdwa v3, v228, sext(v3) dst_sel:DWORD dst_unused:UNUSED_PAD src0_sel:DWORD src1_sel:BYTE_0
	v_ashrrev_i32_e32 v5, 6, v9
	v_and_b32_e32 v9, 0xc0, v9
	v_mul_lo_u32 v8, v8, s41
	v_bfe_i32 v3, v3, 0, 16
	v_add_u32_e32 v10, v5, v6
	v_lshlrev_b32_e32 v6, 5, v4
	v_sub_u32_e32 v7, v7, v9
	v_or_b32_e32 v8, v8, v2
	v_and_b32_e32 v6, 32, v6
	v_ashrrev_i16_sdwa v7, v228, sext(v7) dst_sel:DWORD dst_unused:UNUSED_PAD src0_sel:DWORD src1_sel:BYTE_0
	v_add_lshl_u32 v180, v8, v3, 1
	v_mul_lo_u32 v8, v10, s41
	v_bfe_i32 v7, v7, 0, 16
	v_or_b32_e32 v8, v8, v6
	v_add_u32_e32 v147, 32, v148
	v_add_lshl_u32 v128, v8, v7, 1
	s_mul_i32 s18, s29, 0x84000
	s_mul_hi_i32 s31, s28, 0x1080
	s_mul_i32 s34, s28, 0x1080
	v_add_u32_e32 v146, 0x2000, v147
	v_add_u32_e32 v145, s19, v148
	v_add_u32_e32 v143, 0x4000, v147
	v_add_u32_e32 v142, 0x6000, v147
	s_cbranch_scc1 .LBB0_2563
	s_ashr_i32 s19, s18, 31
	s_lshl_b64 s[20:21], s[18:19], 1
	s_add_u32 s20, s8, s20
	s_addc_u32 s21, s9, s21
	s_add_i32 s19, 32, 0x10000
	v_add_u32_e32 v8, s19, v148
	s_add_u32 s36, s23, s34
	v_readfirstlane_b32 s19, v8
	v_add_u32_e32 v8, 0x2000, v8
	s_mov_b32 m0, s19
	v_readfirstlane_b32 s19, v8
	global_load_lds_dwordx4 v180, s[20:21]
	s_mov_b32 m0, s19
	v_readfirstlane_b32 s19, v147
	global_load_lds_dwordx4 v128, s[20:21]
	s_addc_u32 s37, s24, s31
	s_mov_b32 m0, s19
	v_readfirstlane_b32 s19, v146
	global_load_lds_dwordx4 v180, s[36:37]
	s_mov_b32 m0, s19
	s_add_u32 s20, s20, 0x84000
	v_readfirstlane_b32 s19, v145
	v_add_u32_e32 v8, 0x2000, v145
	global_load_lds_dwordx4 v128, s[36:37]
	s_addc_u32 s21, s21, 0
	s_mov_b32 m0, s19
	v_readfirstlane_b32 s19, v8
	global_load_lds_dwordx4 v180, s[20:21]
	s_mov_b32 m0, s19
	s_or_b32 s19, s28, 0x80
	global_load_lds_dwordx4 v128, s[20:21]
	s_mul_hi_i32 s21, s19, 0x1080
	s_mulk_i32 s19, 0x1080
	s_add_u32 s20, s23, s19
	v_readfirstlane_b32 s19, v143
	s_addc_u32 s21, s24, s21
	s_mov_b32 m0, s19
	v_readfirstlane_b32 s19, v142
	global_load_lds_dwordx4 v180, s[20:21]
	s_mov_b32 m0, s19
	s_nop 0
	global_load_lds_dwordx4 v128, s[20:21]
	s_waitcnt vmcnt(0)

; #define STAGE_A(P, br, kt) do { const char* _base = (const char*)(((kt) < G.ksplit ? G.A1 : A2m) + (long)(br) * G.lda + (long)(kt) * BK); \
;     __builtin_amdgcn_global_load_lds((const unsigned*)(_base + aoff0), (unsigned*)((char*)(P) + sb0), 16, 0, 0); \
;     __builtin_amdgcn_global_load_lds((const unsigned*)(_base + aoff1), (unsigned*)((char*)(P) + sb1), 16, 0, 0); } while (0)
; #define STAGE_B(P, br, kt) do { const char* _base = (const char*)(G.Bt + (long)(br) * G.ldb + (long)(kt) * BK); \
;     __builtin_amdgcn_global_load_lds((const unsigned*)(_base + boff0), (unsigned*)((char*)(P) + sb0), 16, 0, 0); \
;     __builtin_amdgcn_global_load_lds((const unsigned*)(_base + boff1), (unsigned*)((char*)(P) + sb1), 16, 0, 0); } while (0)
; #define WAIT_V(n) asm volatile("s_waitcnt vmcnt(" #n ")" ::: "memory")
; #define BAR __builtin_amdgcn_s_barrier()
;     ...
;   int t1 = otid();
;   const int wid = t1 >> 6, lane = t1 & 63, wr = wid >> 2, wc = wid & 3, fr = lane & 15, fq = lane >> 4;
;   const int sb0 = t1 * 16, sb1 = sb0 + 8192;
;   const int swz_ = lds_byte(fr, fq * 8);
;   const char* a_rd = shmc + wr * 8192 + swz_;
;   const char* b_rd = shmc + 4 * (HT * 2) + wc * 4096 + swz_;
;   int r0_, c0_, r1_, c1_; stage_rc(sb0, r0_, c0_); stage_rc(sb1, r1_, c1_);
;   const unsigned aoff0 = (unsigned)(r0_ * G.lda + c0_) * 2u, aoff1 = (unsigned)(r1_ * G.lda + c1_) * 2u;
;   const unsigned boff0 = (unsigned)(r0_ * G.ldb + c0_) * 2u, boff1 = (unsigned)(r1_ * G.ldb + c1_) * 2u;
;   f32x4 acc[2][2][4][2] = {};
;   bf16x8 At[4][2], B0[2][2], B1[2][2];
;   const int nt = K / BK;
;   if (EPI == EPI_RESID || first) {
;     STAGE_B(SB(0, 0), bcol, 0); STAGE_A(SA(0, 0), brow, 0);
;     STAGE_B(SB(0, 1), bcol + HALF, 0); STAGE_A(SA(0, 1), brow + HALF, 0);
;   }
;   if (wr == 1) BAR;
;   WAIT_V(0); BAR;
;   STAGE_B(SB(1, 0), bcol, 1); STAGE_A(SA(1, 0), brow, 1); STAGE_B(SB(1, 1), bcol + HALF, 1);
;   WAIT_V(6); BAR;
.LBB0_2565:
	s_or_b64 exec, exec, s[20:21]
	v_and_b32_e32 v152, 15, v144
	v_lshlrev_b32_e32 v10, 2, v144
	s_ashr_i32 s19, s18, 31
	v_and_b32_e32 v8, 48, v144
	v_lshlrev_b32_e32 v9, 6, v152
	v_and_b32_e32 v10, 32, v10
	s_add_i32 s21, 32, 0x10000
	s_lshl_b32 s29, s29, 8
	s_lshl_b64 s[36:37], s[18:19], 1
	v_bitop3_b32 v10, v9, v10, v8 bitop3:0x36
	v_lshlrev_b32_e32 v8, 6, v144
	s_add_u32 s38, s8, s36
	v_readlane_b32 s19, v253, 46
	v_and_b32_e32 v8, 0x3000, v8
	s_addc_u32 s39, s9, s37
	v_add_u32_e32 v153, s19, v148
	s_waitcnt vmcnt(16)
	v_add_u32_e32 v12, s21, v8
	v_lshl_add_u64 v[8:9], s[38:39], 0, v[180:181]
	s_mov_b64 s[44:45], 0x80
	v_readfirstlane_b32 s19, v153
	v_lshl_add_u64 v[8:9], v[8:9], 0, s[44:45]
	s_mov_b32 m0, s19
	v_mov_b32_e32 v129, v181
	v_add_u32_e32 v154, 0x2000, v153
	s_waitcnt vmcnt(16)
	s_barrier
	global_load_lds_dwordx4 v[8:9], off
	v_lshl_add_u64 v[8:9], s[38:39], 0, v[128:129]
	v_readfirstlane_b32 s19, v154
	s_add_u32 s34, s23, s34
	v_lshl_add_u64 v[8:9], v[8:9], 0, s[44:45]
	s_mov_b32 m0, s19
	s_addc_u32 s35, s24, s31
	v_add_u32_e32 v155, 0x8000, v147
	global_load_lds_dwordx4 v[8:9], off
	v_lshl_add_u64 v[8:9], s[34:35], 0, v[180:181]
	v_readfirstlane_b32 s19, v155
	v_lshl_add_u64 v[8:9], v[8:9], 0, s[44:45]
	s_mov_b32 m0, s19
	s_or_b32 s20, s29, 0x80
	global_load_lds_dwordx4 v[8:9], off
	v_lshl_add_u64 v[8:9], s[34:35], 0, v[128:129]
	s_mul_i32 s34, s20, 0x840
	v_add_u32_e32 v156, 0xa000, v147
	s_ashr_i32 s35, s34, 31
	v_readfirstlane_b32 s19, v156
	s_lshl_b64 s[34:35], s[34:35], 1
	s_mov_b32 m0, s19
	s_add_u32 s34, s8, s34
	v_readlane_b32 s19, v253, 47
	v_lshl_add_u64 v[8:9], v[8:9], 0, s[44:45]
	s_addc_u32 s35, s9, s35
	v_add_u32_e32 v157, s19, v148
	global_load_lds_dwordx4 v[8:9], off
	v_lshl_add_u64 v[8:9], s[34:35], 0, v[180:181]
	v_readfirstlane_b32 s19, v157
	v_lshl_add_u64 v[8:9], v[8:9], 0, s[44:45]
	s_mov_b32 m0, s19
	v_add_u32_e32 v158, 0x2000, v157
	global_load_lds_dwordx4 v[8:9], off
	v_lshl_add_u64 v[8:9], s[34:35], 0, v[128:129]
	v_readfirstlane_b32 s19, v158
	v_lshl_add_u64 v[8:9], v[8:9], 0, s[44:45]
	s_mov_b32 m0, s19
	s_add_i32 s18, s18, 0x40000
	global_load_lds_dwordx4 v[8:9], off
	v_lshrrev_b32_e32 v8, 1, v0
	v_mul_lo_u32 v0, v1, s41
	v_mad_u64_u32 v[0:1], s[34:35], v8, s84, v[0:1]
	v_or_b32_e32 v0, v0, v2
	v_add_lshl_u32 v0, v0, v3, 1
	v_lshrrev_b32_e32 v3, 1, v4
	v_mul_lo_u32 v2, v5, s41
	v_mad_u64_u32 v[2:3], s[34:35], v3, s84, v[2:3]
	s_ashr_i32 s19, s18, 31
	s_waitcnt vmcnt(6)
	v_mov_b32_e32 v1, v181
	v_or_b32_e32 v2, v2, v6
	s_lshl_b64 s[18:19], s[18:19], 1
	v_lshl_add_u32 v11, v151, 13, 32
	v_lshl_add_u64 v[130:131], s[36:37], 0, v[0:1]
	v_add_lshl_u32 v2, v2, v7, 1
	v_mov_b32_e32 v3, v181
	v_mad_i64_i32 v[134:135], s[34:35], s28, v243, v[0:1]
	v_lshl_add_u64 v[138:139], s[18:19], 0, v[0:1]
	v_mov_b32_e32 v0, 0
	v_mov_b32_e32 v245, 0x80003fff
	v_lshl_add_u64 v[132:133], s[36:37], 0, v[2:3]
	v_mad_i64_i32 v[136:137], s[34:35], s28, v243, v[2:3]
	v_lshl_add_u64 v[140:141], s[18:19], 0, v[2:3]
	s_mov_b32 s31, -2
	v_add_u32_e32 v150, v12, v10
	v_add_u32_e32 v149, v11, v10
	s_mov_b64 s[18:19], s[8:9]
	v_mov_b32_e32 v1, v0
	v_mov_b32_e32 v2, v0
	v_mov_b32_e32 v3, v0
	v_mov_b32_e32 v4, v0
	v_mov_b32_e32 v5, v0
	v_mov_b32_e32 v6, v0
	v_mov_b32_e32 v7, v0
	v_mov_b32_e32 v8, v0
	v_mov_b32_e32 v9, v0
	v_mov_b32_e32 v10, v0
	v_mov_b32_e32 v11, v0
	v_mov_b32_e32 v12, v0
	v_mov_b32_e32 v13, v0
	v_mov_b32_e32 v14, v0
	v_mov_b32_e32 v15, v0
	v_mov_b32_e32 v16, v0
	v_mov_b32_e32 v17, v0
	v_mov_b32_e32 v18, v0
	v_mov_b32_e32 v19, v0
	v_mov_b32_e32 v20, v0
	v_mov_b32_e32 v21, v0
	v_mov_b32_e32 v22, v0
	v_mov_b32_e32 v23, v0
	v_mov_b32_e32 v24, v0
	v_mov_b32_e32 v25, v0
	v_mov_b32_e32 v26, v0
	v_mov_b32_e32 v27, v0
	v_mov_b32_e32 v28, v0
	v_mov_b32_e32 v29, v0
	v_mov_b32_e32 v30, v0
	v_mov_b32_e32 v31, v0
	v_mov_b32_e32 v32, v0
	v_mov_b32_e32 v33, v0
	v_mov_b32_e32 v34, v0
	v_mov_b32_e32 v35, v0
	v_mov_b32_e32 v36, v0
	v_mov_b32_e32 v37, v0
	v_mov_b32_e32 v38, v0
	v_mov_b32_e32 v39, v0
	v_mov_b32_e32 v40, v0
	v_mov_b32_e32 v41, v0
	v_mov_b32_e32 v42, v0
	v_mov_b32_e32 v43, v0
	v_mov_b32_e32 v44, v0
	v_mov_b32_e32 v45, v0
	v_mov_b32_e32 v46, v0
	v_mov_b32_e32 v47, v0
	v_mov_b32_e32 v48, v0
	v_mov_b32_e32 v49, v0
	v_mov_b32_e32 v50, v0
	v_mov_b32_e32 v51, v0
	v_mov_b32_e32 v52, v0
	v_mov_b32_e32 v53, v0
	v_mov_b32_e32 v54, v0
	v_mov_b32_e32 v55, v0
	v_mov_b32_e32 v56, v0
	v_mov_b32_e32 v57, v0
	v_mov_b32_e32 v58, v0
	v_mov_b32_e32 v59, v0
	v_mov_b32_e32 v60, v0
	v_mov_b32_e32 v61, v0
	v_mov_b32_e32 v62, v0
	v_mov_b32_e32 v63, v0
	v_mov_b32_e32 v64, v0
	v_mov_b32_e32 v65, v0
	v_mov_b32_e32 v66, v0
	v_mov_b32_e32 v67, v0
	v_mov_b32_e32 v68, v0
	v_mov_b32_e32 v69, v0
	v_mov_b32_e32 v70, v0
	v_mov_b32_e32 v71, v0
	v_mov_b32_e32 v72, v0
	v_mov_b32_e32 v73, v0
	v_mov_b32_e32 v74, v0
	v_mov_b32_e32 v75, v0
	v_mov_b32_e32 v76, v0
	v_mov_b32_e32 v77, v0
	v_mov_b32_e32 v78, v0
	v_mov_b32_e32 v79, v0
	v_mov_b32_e32 v80, v0
	v_mov_b32_e32 v81, v0
	v_mov_b32_e32 v82, v0
	v_mov_b32_e32 v83, v0
	v_mov_b32_e32 v84, v0
	v_mov_b32_e32 v85, v0
	v_mov_b32_e32 v86, v0
	v_mov_b32_e32 v87, v0
	v_mov_b32_e32 v88, v0
	v_mov_b32_e32 v89, v0
	v_mov_b32_e32 v90, v0
	v_mov_b32_e32 v91, v0
	v_mov_b32_e32 v92, v0
	v_mov_b32_e32 v93, v0
	v_mov_b32_e32 v94, v0
	v_mov_b32_e32 v95, v0
	v_mov_b32_e32 v96, v0
	v_mov_b32_e32 v97, v0
	v_mov_b32_e32 v98, v0
	v_mov_b32_e32 v99, v0
	v_mov_b32_e32 v100, v0
	v_mov_b32_e32 v101, v0
	v_mov_b32_e32 v102, v0
	v_mov_b32_e32 v103, v0
	v_mov_b32_e32 v104, v0
	v_mov_b32_e32 v105, v0
	v_mov_b32_e32 v106, v0
	v_mov_b32_e32 v107, v0
	v_mov_b32_e32 v108, v0
	v_mov_b32_e32 v109, v0
	v_mov_b32_e32 v110, v0
	v_mov_b32_e32 v111, v0
	v_mov_b32_e32 v112, v0
	v_mov_b32_e32 v113, v0
	v_mov_b32_e32 v114, v0
	v_mov_b32_e32 v115, v0
	v_mov_b32_e32 v116, v0
	v_mov_b32_e32 v117, v0
	v_mov_b32_e32 v118, v0
	v_mov_b32_e32 v119, v0
	v_mov_b32_e32 v120, v0
	v_mov_b32_e32 v121, v0
	v_mov_b32_e32 v122, v0
	v_mov_b32_e32 v123, v0
	v_mov_b32_e32 v124, v0
	v_mov_b32_e32 v125, v0
	v_mov_b32_e32 v126, v0
	v_mov_b32_e32 v127, v0
	s_barrier
